# softplus(-lambda) table computed once in prep (same log1p instruction sequence) and loaded in the RG-LRU items instead of recomputing it 4x per thread per item
# speedup vs baseline: 1.0140x; 1.0140x over previous
; __device__ __forceinline__ bf16_t f2bf(float f) { return (bf16_t)(cvt_pk_bf16(f, 0.f) & 0xffffu); }
; __device__ __forceinline__ float bf2f(bf16_t b) { return __uint_as_float(((unsigned)b) << 16); }
; template <int APPLY>
; __device__ void lru_item(PP p, int l, int bb, int ck, int nb, unsigned epoch) {
;     ...
;     const bf16_t* wsrc = p->lruWT + (long)((l * 8 + nb) * 2) * 4096;
;     const int d = tid >> 3, c8 = (tid & 7) * 8;
;     *(uint4*)(wta + d * 72 + c8) = *(const uint4*)(wsrc + d * 64 + c8);
;     *(uint4*)(wtx + d * 72 + c8) = *(const uint4*)(wsrc + 4096 + d * 64 + c8);
;   }
;   __syncthreads();
;   {
;     const int ch = tid & 63, gch = nb * 64 + ch;
;     const float* cw = p->conv_w + (long)l * 4 * 512 + gch;
;     const float w0 = cw[0], w1 = cw[512], w2 = cw[1024], w3 = cw[1536], cb = p->conv_b[l * 512 + gch];
; #pragma unroll
;     for (int i = 0; i < 16; ++i) {
;       const int tok = (tid >> 6) + 8 * i;
;       const float v = cb + w0 * bf2f(cxs[(tok + 0) * 64 + ch]) + w1 * bf2f(cxs[(tok + 1) * 64 + ch]) +
;                       w2 * bf2f(cxs[(tok + 2) * 64 + ch]) + w3 * bf2f(cxs[(tok + 3) * 64 + ch]);
;       xcs[tok * 72 + ch] = f2bf(v);
;     }
;   }
;     ...
;       const float ba_ = p->lru_b_a[l * 512 + gch], bx_ = p->lru_b_x[l * 512 + gch];
;       const float sp = log1pf(__expf(-p->lru_lambda[l * 512 + gch]));
.LBB0_122:
	s_or_b64 exec, exec, s[4:5]
	s_load_dwordx4 s[40:43], s[0:1], 0x110
	s_mov_b64 s[4:5], 0x1e00
	v_lshl_add_u64 v[22:23], v[6:7], 0, s[4:5]
	s_lshl_b32 s4, s6, 14
	s_or_b32 s4, s4, s74
	v_ashrrev_i32_e32 v4, 3, v24
	s_waitcnt lgkmcnt(0)
	s_add_u32 s4, s40, s4
	v_lshlrev_b32_e32 v2, 6, v4
	s_addc_u32 s5, s41, 0
	v_ashrrev_i32_e32 v3, 31, v2
	v_lshlrev_b32_e32 v0, 4, v24
	v_lshl_add_u64 v[2:3], v[2:3], 1, s[4:5]
	v_and_b32_e32 v0, 0x70, v0
	s_movk_i32 s8, 0x90
	v_lshl_add_u64 v[6:7], v[2:3], 0, v[0:1]
	v_mul_lo_u32 v2, v4, s8
	v_add3_u32 v0, 0, v2, v0
	global_load_dwordx4 v[2:5], v[6:7], off
	s_movk_i32 s4, 0x2000
	v_or_b32_e32 v8, s89, v71
	s_movk_i32 s6, 0x1000
	v_and_b32_e32 v30, 15, v24
	v_mov_b32_e32 v55, 0x3ecc95a3
	s_mov_b32 s13, 0x7f800000
	v_mov_b32_e32 v57, 0x7f800000
	v_mov_b32_e32 v73, 0x7fc00000
	v_mov_b32_e32 v74, 0xff800000
	s_mov_b32 s30, 0x33800000
	s_mov_b32 s31, 0xf800000
	v_mov_b32_e32 v56, 0x260
	s_waitcnt vmcnt(0)
	ds_write_b128 v0, v[2:5] offset:35328
	v_add_co_u32_e32 v2, vcc, s4, v6
	s_nop 1
	v_addc_co_u32_e32 v3, vcc, 0, v7, vcc
	global_load_dwordx4 v[2:5], v[2:3], off
	s_waitcnt vmcnt(0)
	ds_write_b128 v0, v[2:5] offset:44544
	s_waitcnt lgkmcnt(0)
	s_barrier
	s_load_dwordx4 s[44:47], s[0:1], 0x38
	s_load_dwordx2 s[56:57], s[0:1], 0x50
	s_load_dwordx2 s[48:49], s[0:1], 0x60
	s_load_dwordx2 s[50:51], s[0:1], 0xf8
	v_lshlrev_b32_e32 v0, 2, v8
	s_waitcnt lgkmcnt(0)
	s_add_u32 s40, s44, s78
	s_addc_u32 s41, s45, 0
	v_lshl_add_u64 v[2:3], s[40:41], 0, v[0:1]
	global_load_dword v7, v0, s[40:41]
	global_load_dword v5, v0, s[40:41] offset:2048
	v_add_co_u32_e32 v2, vcc, s6, v2
	v_or_b32_e32 v0, s60, v8
	s_nop 0
	v_addc_co_u32_e32 v3, vcc, 0, v3, vcc
	v_lshlrev_b32_e32 v0, 2, v0
	global_load_dword v6, v[2:3], off
	global_load_dword v4, v[2:3], off offset:2048
	global_load_dword v8, v0, s[46:47]
	v_lshlrev_b32_e32 v2, 1, v24
	v_add_u32_e32 v0, 0, v18
	v_and_b32_e32 v2, 0xffffff80, v2
	v_add_u32_e32 v3, v0, v2
	ds_read_u16 v3, v3
	v_add3_u32 v2, 0, v2, v18
	ds_read_u16 v9, v2 offset:128
	s_waitcnt lgkmcnt(1)
	v_lshlrev_b32_e32 v3, 16, v3
	s_waitcnt lgkmcnt(0)
	v_lshlrev_b32_e32 v9, 16, v9
	s_waitcnt vmcnt(0)
	v_fma_f32 v3, v7, v3, v8
	v_fmac_f32_e32 v3, v5, v9
	ds_read_u16 v9, v2 offset:256
	ds_read_u16 v2, v2 offset:384
	s_waitcnt lgkmcnt(1)
	v_lshlrev_b32_e32 v9, 16, v9
	v_fmac_f32_e32 v3, v6, v9
	s_waitcnt lgkmcnt(0)
	v_lshlrev_b32_e32 v2, 16, v2
	v_fmac_f32_e32 v3, v4, v2
	v_cvt_pk_bf16_f32 v9, v3, s0
	v_mad_u64_u32 v[2:3], s[4:5], v27, s8, v[0:1]
	v_lshlrev_b32_e32 v3, 7, v27
	ds_write_b16 v2, v9 offset:16896
	v_add_u32_e32 v9, 0x400, v3
	v_add_u32_e32 v10, v0, v9
	ds_read_u16 v10, v10
	v_add3_u32 v9, 0, v9, v18
	ds_read_u16 v11, v9 offset:128
	s_mov_b32 s5, 0x3f2aaaab
	s_movk_i32 s4, 0x300
	s_waitcnt lgkmcnt(1)
	v_lshlrev_b32_e32 v10, 16, v10
	v_fma_f32 v10, v7, v10, v8
	s_waitcnt lgkmcnt(0)
	v_lshlrev_b32_e32 v11, 16, v11
	v_fmac_f32_e32 v10, v5, v11
	ds_read_u16 v11, v9 offset:256
	ds_read_u16 v9, v9 offset:384
	s_waitcnt lgkmcnt(1)
	v_lshlrev_b32_e32 v11, 16, v11
	v_fmac_f32_e32 v10, v6, v11
	s_waitcnt lgkmcnt(0)
	v_lshlrev_b32_e32 v9, 16, v9
	v_fmac_f32_e32 v10, v4, v9
	v_cvt_pk_bf16_f32 v9, v10, s0
	ds_write_b16 v2, v9 offset:18048
	v_add_u32_e32 v9, 0x800, v3
	v_add_u32_e32 v10, v0, v9
	ds_read_u16 v10, v10
	v_add3_u32 v9, 0, v9, v18
	ds_read_u16 v11, v9 offset:128
	s_waitcnt lgkmcnt(1)
	v_lshlrev_b32_e32 v10, 16, v10
	v_fma_f32 v10, v7, v10, v8
	s_waitcnt lgkmcnt(0)
	v_lshlrev_b32_e32 v11, 16, v11
	v_fmac_f32_e32 v10, v5, v11
	ds_read_u16 v11, v9 offset:256
	ds_read_u16 v9, v9 offset:384
	s_waitcnt lgkmcnt(1)
	v_lshlrev_b32_e32 v11, 16, v11
	v_fmac_f32_e32 v10, v6, v11
	s_waitcnt lgkmcnt(0)
	v_lshlrev_b32_e32 v9, 16, v9
	v_fmac_f32_e32 v10, v4, v9
	v_cvt_pk_bf16_f32 v9, v10, s0
	ds_write_b16 v2, v9 offset:19200
	v_add_u32_e32 v9, 0xc00, v3
	v_add_u32_e32 v10, v0, v9
	ds_read_u16 v10, v10
	v_add3_u32 v9, 0, v9, v18
	ds_read_u16 v11, v9 offset:128
	s_waitcnt lgkmcnt(1)
	v_lshlrev_b32_e32 v10, 16, v10
	v_fma_f32 v10, v7, v10, v8
	s_waitcnt lgkmcnt(0)
	v_lshlrev_b32_e32 v11, 16, v11
	v_fmac_f32_e32 v10, v5, v11
	ds_read_u16 v11, v9 offset:256
	ds_read_u16 v9, v9 offset:384
	s_waitcnt lgkmcnt(1)
	v_lshlrev_b32_e32 v11, 16, v11
	v_fmac_f32_e32 v10, v6, v11
	s_waitcnt lgkmcnt(0)
	v_lshlrev_b32_e32 v9, 16, v9
	v_fmac_f32_e32 v10, v4, v9
	v_cvt_pk_bf16_f32 v9, v10, s0
	ds_write_b16 v2, v9 offset:20352
	v_add_u32_e32 v9, 0x1000, v3
	v_add_u32_e32 v10, v0, v9
	ds_read_u16 v10, v10
	v_add3_u32 v9, 0, v9, v18
	ds_read_u16 v11, v9 offset:128
	s_waitcnt lgkmcnt(1)
	v_lshlrev_b32_e32 v10, 16, v10
	v_fma_f32 v10, v7, v10, v8
	s_waitcnt lgkmcnt(0)
	v_lshlrev_b32_e32 v11, 16, v11
	v_fmac_f32_e32 v10, v5, v11
	ds_read_u16 v11, v9 offset:256
	ds_read_u16 v9, v9 offset:384
	s_waitcnt lgkmcnt(1)
	v_lshlrev_b32_e32 v11, 16, v11
	v_fmac_f32_e32 v10, v6, v11
	s_waitcnt lgkmcnt(0)
	v_lshlrev_b32_e32 v9, 16, v9
	v_fmac_f32_e32 v10, v4, v9
	v_cvt_pk_bf16_f32 v9, v10, s0
	ds_write_b16 v2, v9 offset:21504
	v_add_u32_e32 v9, 0x1400, v3
	v_add_u32_e32 v10, v0, v9
	ds_read_u16 v10, v10
	v_add3_u32 v9, 0, v9, v18
	ds_read_u16 v11, v9 offset:128
	s_waitcnt lgkmcnt(1)
	v_lshlrev_b32_e32 v10, 16, v10
	v_fma_f32 v10, v7, v10, v8
	s_waitcnt lgkmcnt(0)
	v_lshlrev_b32_e32 v11, 16, v11
	v_fmac_f32_e32 v10, v5, v11
	ds_read_u16 v11, v9 offset:256
	ds_read_u16 v9, v9 offset:384
	s_waitcnt lgkmcnt(1)
	v_lshlrev_b32_e32 v11, 16, v11
	v_fmac_f32_e32 v10, v6, v11
	s_waitcnt lgkmcnt(0)
	v_lshlrev_b32_e32 v9, 16, v9
	v_fmac_f32_e32 v10, v4, v9
	v_cvt_pk_bf16_f32 v9, v10, s0
	ds_write_b16 v2, v9 offset:22656
	v_add_u32_e32 v9, 0x1800, v3
	v_add_u32_e32 v10, v0, v9
	ds_read_u16 v10, v10
	v_add3_u32 v9, 0, v9, v18
	ds_read_u16 v11, v9 offset:128
	s_waitcnt lgkmcnt(1)
; __device__ __forceinline__ bf16_t f2bf(float f) { return (bf16_t)(cvt_pk_bf16(f, 0.f) & 0xffffu); }
; __device__ __forceinline__ float bf2f(bf16_t b) { return __uint_as_float(((unsigned)b) << 16); }
; template <int APPLY>
; __device__ void lru_item(PP p, int l, int bb, int ck, int nb, unsigned epoch) {
;     ...
; #pragma unroll
;     for (int i = 0; i < 16; ++i) {
;       const int tok = (tid >> 6) + 8 * i;
;       const float v = cb + w0 * bf2f(cxs[(tok + 0) * 64 + ch]) + w1 * bf2f(cxs[(tok + 1) * 64 + ch]) +
;                       w2 * bf2f(cxs[(tok + 2) * 64 + ch]) + w3 * bf2f(cxs[(tok + 3) * 64 + ch]);
;       xcs[tok * 72 + ch] = f2bf(v);
;     }
;   }
;   __syncthreads();
	v_lshlrev_b32_e32 v10, 16, v10
	v_fma_f32 v10, v7, v10, v8
	s_waitcnt lgkmcnt(0)
	v_lshlrev_b32_e32 v11, 16, v11
	v_fmac_f32_e32 v10, v5, v11
	ds_read_u16 v11, v9 offset:256
	ds_read_u16 v9, v9 offset:384
	s_waitcnt lgkmcnt(1)
	v_lshlrev_b32_e32 v11, 16, v11
	v_fmac_f32_e32 v10, v6, v11
	s_waitcnt lgkmcnt(0)
	v_lshlrev_b32_e32 v9, 16, v9
	v_fmac_f32_e32 v10, v4, v9
	v_cvt_pk_bf16_f32 v9, v10, s0
	ds_write_b16 v2, v9 offset:23808
	v_add_u32_e32 v9, 0x1c00, v3
	v_add_u32_e32 v10, v0, v9
	ds_read_u16 v10, v10
	v_add3_u32 v9, 0, v9, v18
	ds_read_u16 v11, v9 offset:128
	s_waitcnt lgkmcnt(1)
	v_lshlrev_b32_e32 v10, 16, v10
	v_fma_f32 v10, v7, v10, v8
	s_waitcnt lgkmcnt(0)
	v_lshlrev_b32_e32 v11, 16, v11
	v_fmac_f32_e32 v10, v5, v11
	ds_read_u16 v11, v9 offset:256
	ds_read_u16 v9, v9 offset:384
	s_waitcnt lgkmcnt(1)
	v_lshlrev_b32_e32 v11, 16, v11
	v_fmac_f32_e32 v10, v6, v11
	s_waitcnt lgkmcnt(0)
	v_lshlrev_b32_e32 v9, 16, v9
	v_fmac_f32_e32 v10, v4, v9
	v_cvt_pk_bf16_f32 v9, v10, s0
	ds_write_b16 v2, v9 offset:24960
	v_add_u32_e32 v9, 0x2000, v3
	v_add_u32_e32 v10, v0, v9
	ds_read_u16 v10, v10
	v_add3_u32 v9, 0, v9, v18
	ds_read_u16 v11, v9 offset:128
	s_waitcnt lgkmcnt(1)
	v_lshlrev_b32_e32 v10, 16, v10
	v_fma_f32 v10, v7, v10, v8
	s_waitcnt lgkmcnt(0)
	v_lshlrev_b32_e32 v11, 16, v11
	v_fmac_f32_e32 v10, v5, v11
	ds_read_u16 v11, v9 offset:256
	ds_read_u16 v9, v9 offset:384
	s_waitcnt lgkmcnt(1)
	v_lshlrev_b32_e32 v11, 16, v11
	v_fmac_f32_e32 v10, v6, v11
	s_waitcnt lgkmcnt(0)
	v_lshlrev_b32_e32 v9, 16, v9
	v_fmac_f32_e32 v10, v4, v9
	v_cvt_pk_bf16_f32 v9, v10, s0
	ds_write_b16 v2, v9 offset:26112
	v_add_u32_e32 v9, 0x2400, v3
	v_add_u32_e32 v10, v0, v9
	ds_read_u16 v10, v10
	v_add3_u32 v9, 0, v9, v18
	ds_read_u16 v11, v9 offset:128
	s_waitcnt lgkmcnt(1)
	v_lshlrev_b32_e32 v10, 16, v10
	v_fma_f32 v10, v7, v10, v8
	s_waitcnt lgkmcnt(0)
	v_lshlrev_b32_e32 v11, 16, v11
	v_fmac_f32_e32 v10, v5, v11
	ds_read_u16 v11, v9 offset:256
	ds_read_u16 v9, v9 offset:384
	s_waitcnt lgkmcnt(1)
	v_lshlrev_b32_e32 v11, 16, v11
	v_fmac_f32_e32 v10, v6, v11
	s_waitcnt lgkmcnt(0)
	v_lshlrev_b32_e32 v9, 16, v9
	v_fmac_f32_e32 v10, v4, v9
	v_cvt_pk_bf16_f32 v9, v10, s0
	ds_write_b16 v2, v9 offset:27264
	v_add_u32_e32 v9, 0x2800, v3
	v_add_u32_e32 v10, v0, v9
	ds_read_u16 v10, v10
	v_add3_u32 v9, 0, v9, v18
	ds_read_u16 v11, v9 offset:128
	s_waitcnt lgkmcnt(1)
	v_lshlrev_b32_e32 v10, 16, v10
	v_fma_f32 v10, v7, v10, v8
	s_waitcnt lgkmcnt(0)
	v_lshlrev_b32_e32 v11, 16, v11
	v_fmac_f32_e32 v10, v5, v11
	ds_read_u16 v11, v9 offset:256
	ds_read_u16 v9, v9 offset:384
	s_waitcnt lgkmcnt(1)
	v_lshlrev_b32_e32 v11, 16, v11
	v_fmac_f32_e32 v10, v6, v11
	s_waitcnt lgkmcnt(0)
	v_lshlrev_b32_e32 v9, 16, v9
	v_fmac_f32_e32 v10, v4, v9
	v_cvt_pk_bf16_f32 v9, v10, s0
	ds_write_b16 v2, v9 offset:28416
	v_add_u32_e32 v9, 0x2c00, v3
	v_add_u32_e32 v10, v0, v9
	ds_read_u16 v10, v10
	v_add3_u32 v9, 0, v9, v18
	ds_read_u16 v11, v9 offset:128
	s_waitcnt lgkmcnt(1)
	v_lshlrev_b32_e32 v10, 16, v10
	v_fma_f32 v10, v7, v10, v8
	s_waitcnt lgkmcnt(0)
	v_lshlrev_b32_e32 v11, 16, v11
	v_fmac_f32_e32 v10, v5, v11
	ds_read_u16 v11, v9 offset:256
	ds_read_u16 v9, v9 offset:384
	s_waitcnt lgkmcnt(1)
	v_lshlrev_b32_e32 v11, 16, v11
	v_fmac_f32_e32 v10, v6, v11
	s_waitcnt lgkmcnt(0)
	v_lshlrev_b32_e32 v9, 16, v9
	v_fmac_f32_e32 v10, v4, v9
	v_cvt_pk_bf16_f32 v9, v10, s0
	ds_write_b16 v2, v9 offset:29568
	v_add_u32_e32 v9, 0x3000, v3
	v_add_u32_e32 v10, v0, v9
	ds_read_u16 v10, v10
	v_add3_u32 v9, 0, v9, v18
	ds_read_u16 v11, v9 offset:128
	s_waitcnt lgkmcnt(1)
	v_lshlrev_b32_e32 v10, 16, v10
	v_fma_f32 v10, v7, v10, v8
	s_waitcnt lgkmcnt(0)
	v_lshlrev_b32_e32 v11, 16, v11
	v_fmac_f32_e32 v10, v5, v11
	ds_read_u16 v11, v9 offset:256
	ds_read_u16 v9, v9 offset:384
	s_waitcnt lgkmcnt(1)
	v_lshlrev_b32_e32 v11, 16, v11
	v_fmac_f32_e32 v10, v6, v11
	s_waitcnt lgkmcnt(0)
	v_lshlrev_b32_e32 v9, 16, v9
	v_fmac_f32_e32 v10, v4, v9
	v_cvt_pk_bf16_f32 v9, v10, s0
	ds_write_b16 v2, v9 offset:30720
	v_add_u32_e32 v9, 0x3400, v3
	v_add_u32_e32 v10, v0, v9
	ds_read_u16 v10, v10
	v_add3_u32 v9, 0, v9, v18
	ds_read_u16 v11, v9 offset:128
	s_waitcnt lgkmcnt(1)
	v_lshlrev_b32_e32 v10, 16, v10
	v_fma_f32 v10, v7, v10, v8
	s_waitcnt lgkmcnt(0)
	v_lshlrev_b32_e32 v11, 16, v11
	v_fmac_f32_e32 v10, v5, v11
	ds_read_u16 v11, v9 offset:256
	ds_read_u16 v9, v9 offset:384
	s_waitcnt lgkmcnt(1)
	v_lshlrev_b32_e32 v11, 16, v11
	v_fmac_f32_e32 v10, v6, v11
	s_waitcnt lgkmcnt(0)
	v_lshlrev_b32_e32 v9, 16, v9
	v_fmac_f32_e32 v10, v4, v9
	v_cvt_pk_bf16_f32 v9, v10, s0
	ds_write_b16 v2, v9 offset:31872
	v_add_u32_e32 v9, 0x3800, v3
	v_add_u32_e32 v10, v0, v9
	ds_read_u16 v10, v10
	v_add3_u32 v9, 0, v9, v18
	ds_read_u16 v11, v9 offset:128
	v_add_u32_e32 v3, 0x3c00, v3
	v_add_u32_e32 v0, v0, v3
	s_waitcnt lgkmcnt(1)
	v_lshlrev_b32_e32 v10, 16, v10
	v_fma_f32 v10, v7, v10, v8
	s_waitcnt lgkmcnt(0)
	v_lshlrev_b32_e32 v11, 16, v11
	v_fmac_f32_e32 v10, v5, v11
	ds_read_u16 v11, v9 offset:256
	ds_read_u16 v9, v9 offset:384
	s_waitcnt lgkmcnt(1)
	v_lshlrev_b32_e32 v11, 16, v11
	v_fmac_f32_e32 v10, v6, v11
	s_waitcnt lgkmcnt(0)
	v_lshlrev_b32_e32 v9, 16, v9
	v_fmac_f32_e32 v10, v4, v9
	v_cvt_pk_bf16_f32 v9, v10, s0
	ds_write_b16 v2, v9 offset:33024
	ds_read_u16 v0, v0
	s_waitcnt lgkmcnt(0)
	v_lshlrev_b32_e32 v0, 16, v0
	v_fmac_f32_e32 v8, v7, v0
	v_add3_u32 v0, 0, v3, v18
	ds_read_u16 v3, v0 offset:128
	s_waitcnt lgkmcnt(0)
	v_lshlrev_b32_e32 v3, 16, v3
	v_fmac_f32_e32 v8, v5, v3
	ds_read_u16 v3, v0 offset:256
	ds_read_u16 v0, v0 offset:384
	s_waitcnt lgkmcnt(1)
	v_lshlrev_b32_e32 v3, 16, v3
	v_fmac_f32_e32 v8, v6, v3
	s_waitcnt lgkmcnt(0)
	v_lshlrev_b32_e32 v0, 16, v0
	v_fmac_f32_e32 v8, v4, v0
	v_cvt_pk_bf16_f32 v0, v8, s0
	ds_write_b16 v2, v0 offset:34176
	v_or_b32_e32 v0, v20, v30
	v_mul_lo_u32 v0, v0, s8
	v_and_b32_e32 v2, 48, v24
	v_add3_u32 v0, 0, v0, v2
	s_waitcnt lgkmcnt(0)
	s_barrier
; __device__ __forceinline__ float bf2f(bf16_t b) { return __uint_as_float(((unsigned)b) << 16); }
; __device__ __forceinline__ float sigmoidf_(float x) { return frcp(1.0f + fexp2(-x * LOG2E)); }
; template <int APPLY>
; __device__ void lru_item(PP p, int l, int bb, int ck, int nb, unsigned epoch) {
;     ...
;     bf16x8 a[2];
; #pragma unroll
;     for (int ks = 0; ks < 2; ++ks) a[ks] = *(const bf16x8*)(xcs + (wid * 16 + fr) * 72 + ks * 32 + fq * 8);
; #pragma unroll
;     for (int nk = 0; nk < 4; ++nk) {
;       f32x4 ra = f32x4{0.f, 0.f, 0.f, 0.f}, ia = f32x4{0.f, 0.f, 0.f, 0.f};
; #pragma unroll
;       for (int ks = 0; ks < 2; ++ks) {
;         bf16x8 ba = *(const bf16x8*)(wta + (nk * 16 + fr) * 72 + ks * 32 + fq * 8);
;         bf16x8 bx = *(const bf16x8*)(wtx + (nk * 16 + fr) * 72 + ks * 32 + fq * 8);
;         ra = __builtin_amdgcn_mfma_f32_16x16x32_bf16(a[ks], ba, ra, 0, 0, 0);
;         ia = __builtin_amdgcn_mfma_f32_16x16x32_bf16(a[ks], bx, ia, 0, 0, 0);
;       }
;       const int ch = nk * 16 + fr, gch = nb * 64 + ch;
;       const float ba_ = p->lru_b_a[l * 512 + gch], bx_ = p->lru_b_x[l * 512 + gch];
;       const float sp = log1pf(__expf(-p->lru_lambda[l * 512 + gch]));
;       const float* cw = p->conv_w + (long)l * 4 * 512 + gch;
;       const float w0 = cw[0], w1 = cw[512], w2 = cw[1024], w3 = cw[1536], cb = p->conv_b[l * 512 + gch];
; #pragma unroll
;       for (int reg = 0; reg < 4; ++reg) {
;         const int tok = wid * 16 + 4 * fq + reg;
;         const float r = sigmoidf_(ra[reg] + ba_), ig = sigmoidf_(ia[reg] + bx_);
;         const float log_a = -8.0f * r * sp;
;         const float av = __expf(log_a);
;         const float mult = sqrtf(fmaxf(1.0f - __expf(2.0f * log_a), 0.f));
;         const float xc = cb + w0 * bf2f(cxs[(tok + 0) * 64 + ch]) + w1 * bf2f(cxs[(tok + 1) * 64 + ch]) +
;                          w2 * bf2f(cxs[(tok + 2) * 64 + ch]) + w3 * bf2f(cxs[(tok + 3) * 64 + ch]);
;         as_[tok * 64 + ch] = av;
;         bs_[tok * 64 + ch] = mult * ig * xc;
;       }
	ds_read_b128 v[6:9], v0 offset:16896
	ds_read_b128 v[2:5], v0 offset:16960
	v_and_b32_e32 v0, 48, v71
	v_add_u32_e32 v34, 0, v0
	v_mul_u32_u24_e32 v0, 0x48, v30
	v_lshl_add_u32 v0, v0, 1, v34
	ds_read_b128 v[10:13], v0 offset:35328
	ds_read_b128 v[14:17], v0 offset:44544
	s_waitcnt lgkmcnt(0)
	v_mfma_f32_16x16x32_bf16 v[36:39], v[6:9], v[14:17], 0
	ds_read_b128 v[14:17], v0 offset:35392
	ds_read_b128 v[40:43], v0 offset:44608
	v_or_b32_e32 v0, s89, v30
	v_or_b32_e32 v25, s60, v0
	v_lshlrev_b32_e32 v25, 2, v25
	global_load_dword v29, v25, s[56:57]
	global_load_dword v28, v25, s[48:49]
	global_load_dword v26, v25, s[50:51]
	v_mfma_f32_16x16x32_bf16 v[10:13], v[6:9], v[10:13], 0
	s_mov_b32 s8, 0x3f317218
	v_lshlrev_b32_e32 v0, 2, v0
	s_waitcnt vmcnt(0)
	s_waitcnt lgkmcnt(1)
	v_mfma_f32_16x16x32_bf16 v[14:17], v[2:5], v[14:17], v[10:13]
	s_waitcnt lgkmcnt(0)
	v_mfma_f32_16x16x32_bf16 v[10:13], v[2:5], v[40:43], v[36:39]
	s_nop 5
	v_add_f32_e32 v14, v14, v29
	v_mul_f32_e32 v14, 0xbfb8aa3b, v14
	v_exp_f32_e32 v14, v14
	s_nop 4
	v_add_f32_e32 v10, v10, v28
	v_lshl_add_u64 v[36:37], s[40:41], 0, v[0:1]
	global_load_dword v39, v0, s[40:41]
	global_load_dword v40, v0, s[40:41] offset:2048
	v_add_f32_e32 v14, 1.0, v14
	v_rcp_f32_e32 v14, v14
	v_mul_f32_e32 v10, 0xbfb8aa3b, v10
	v_mul_f32_e32 v14, 0xc1000000, v14
	v_mov_b32_e32 v33, v26
	v_add_co_u32_e32 v36, vcc, s6, v36
	v_exp_f32_e32 v10, v10
	s_nop 0
	v_addc_co_u32_e32 v37, vcc, 0, v37, vcc
	global_load_dword v42, v[36:37], off
	global_load_dword v41, v[36:37], off offset:2048
	global_load_dword v0, v25, s[46:47]
	v_mul_f32_e32 v25, v14, v33
	v_mul_f32_e32 v14, 0x3fb8aa3b, v25
	v_add_f32_e32 v25, v25, v25
	v_mul_f32_e32 v25, 0x3fb8aa3b, v25
	v_exp_f32_e32 v25, v25
	v_add_f32_e32 v10, 1.0, v10
	v_rcp_f32_e32 v10, v10
	v_exp_f32_e32 v14, v14
	v_sub_f32_e32 v25, 1.0, v25
	v_max_f32_e32 v25, 0, v25
	v_cmp_gt_f32_e32 vcc, s31, v25
	v_mul_f32_e32 v26, 0x4f800000, v25
	v_add_f32_e32 v11, v11, v28
	v_cndmask_b32_e32 v25, v25, v26, vcc
	v_sqrt_f32_e32 v26, v25
	v_mul_f32_e32 v11, 0xbfb8aa3b, v11
	v_exp_f32_e32 v11, v11
	v_add_u32_e32 v31, -1, v26
	v_fma_f32 v32, -v31, v26, v25
	v_cmp_ge_f32_e64 s[38:39], 0, v32
	v_add_u32_e32 v32, 1, v26
	v_add_f32_e32 v11, 1.0, v11
	v_cndmask_b32_e64 v31, v26, v31, s[38:39]
	v_fma_f32 v26, -v32, v26, v25
	v_cmp_lt_f32_e64 s[38:39], 0, v26
	v_rcp_f32_e32 v11, v11
	s_nop 0
	v_cndmask_b32_e64 v26, v31, v32, s[38:39]
	v_mul_f32_e32 v31, 0x37800000, v26
	v_cndmask_b32_e32 v26, v26, v31, vcc
	v_cmp_class_f32_e32 vcc, v25, v56
	s_nop 1
	v_cndmask_b32_e32 v32, v26, v25, vcc
	v_lshlrev_b32_e32 v26, 4, v71
	v_lshlrev_b32_e32 v25, 10, v27
	v_and_or_b32 v38, v26, s4, v25
	v_or_b32_e32 v36, v38, v30
	v_lshlrev_b32_e32 v37, 1, v36
	v_add_u32_e32 v43, 0, v37
	ds_read_u16 v31, v43
	v_lshl_add_u32 v35, v38, 1, 0
	v_add_u32_e32 v37, v43, v37
	ds_write_b32 v37, v14 offset:53760
	v_mul_f32_e32 v10, v10, v32
	s_waitcnt lgkmcnt(1)
	v_lshlrev_b32_e32 v31, 16, v31
	v_lshlrev_b32_e32 v14, 2, v36
	v_readlane_b32 s4, v255, 45
	s_waitcnt vmcnt(0)
	v_fma_f32 v44, v39, v31, v0
	v_lshl_add_u32 v31, v30, 1, v35
	ds_read_u16 v45, v31 offset:128
	ds_read_u16 v46, v31 offset:256
	ds_read_u16 v47, v31 offset:384
	v_add_u32_e32 v32, s4, v14
	s_waitcnt lgkmcnt(2)
	v_lshlrev_b32_e32 v45, 16, v45
	v_fmac_f32_e32 v44, v40, v45
	s_waitcnt lgkmcnt(1)
	v_lshlrev_b32_e32 v46, 16, v46
	v_fmac_f32_e32 v44, v42, v46
	s_waitcnt lgkmcnt(0)
	v_lshlrev_b32_e32 v47, 16, v47
	v_fmac_f32_e32 v44, v41, v47
	v_mul_f32_e32 v10, v44, v10
	ds_write_b32 v32, v10
	v_add_f32_e32 v10, v15, v29
	v_mul_f32_e32 v10, 0xbfb8aa3b, v10
	v_exp_f32_e32 v10, v10
	v_fma_f32 v43, v39, v45, v0
	v_fmac_f32_e32 v43, v40, v46
	v_fmac_f32_e32 v43, v42, v47
	v_add_f32_e32 v10, 1.0, v10
	v_rcp_f32_e32 v10, v10
	s_nop 0
	v_mul_f32_e32 v10, 0xc1000000, v10
	v_mul_f32_e32 v10, v10, v33
	v_mul_f32_e32 v15, 0x3fb8aa3b, v10
	v_add_f32_e32 v10, v10, v10
	v_mul_f32_e32 v10, 0x3fb8aa3b, v10
	v_exp_f32_e32 v10, v10
	v_exp_f32_e32 v15, v15
	v_sub_f32_e32 v10, 1.0, v10
	v_max_f32_e32 v10, 0, v10
	v_cmp_gt_f32_e32 vcc, s31, v10
	v_mul_f32_e32 v32, 0x4f800000, v10
	s_nop 0
	v_cndmask_b32_e32 v10, v10, v32, vcc
	v_sqrt_f32_e32 v32, v10
	s_nop 0
	v_add_u32_e32 v36, -1, v32
	v_fma_f32 v37, -v36, v32, v10
	v_cmp_ge_f32_e64 s[38:39], 0, v37
	v_add_u32_e32 v37, 1, v32
	s_nop 0
	v_cndmask_b32_e64 v36, v32, v36, s[38:39]
	v_fma_f32 v32, -v37, v32, v10
	v_cmp_lt_f32_e64 s[38:39], 0, v32
	s_nop 1
	v_cndmask_b32_e64 v32, v36, v37, s[38:39]
	ds_read_u16 v37, v31 offset:512
	v_mul_f32_e32 v36, 0x37800000, v32
	v_cndmask_b32_e32 v32, v32, v36, vcc
	v_cmp_class_f32_e32 vcc, v10, v56
	v_or_b32_e32 v36, 64, v38
	s_waitcnt lgkmcnt(0)
	v_lshlrev_b32_e32 v44, 16, v37
	v_cndmask_b32_e32 v10, v32, v10, vcc
	v_or_b32_e32 v32, v36, v30
	v_fmac_f32_e32 v43, v41, v44
	v_mul_f32_e32 v10, v11, v10
	v_add_u32_e32 v37, 0, v14
	v_mul_f32_e32 v10, v43, v10
	v_lshl_add_u32 v11, v32, 2, s4
	ds_write_b32 v37, v15 offset:54016
	ds_write_b32 v11, v10
	v_add_f32_e32 v10, v16, v29
	v_mul_f32_e32 v10, 0xbfb8aa3b, v10
	v_exp_f32_e32 v10, v10
	v_add_f32_e32 v11, v12, v28
	v_mul_f32_e32 v11, 0xbfb8aa3b, v11
	v_exp_f32_e32 v11, v11
	v_add_f32_e32 v10, 1.0, v10
	v_rcp_f32_e32 v10, v10
	v_or_b32_e32 v32, 0x80, v38
	v_add_f32_e32 v11, 1.0, v11
	v_rcp_f32_e32 v11, v11
	v_mul_f32_e32 v10, 0xc1000000, v10
	v_mul_f32_e32 v10, v10, v33
	v_mul_f32_e32 v12, 0x3fb8aa3b, v10
	v_add_f32_e32 v10, v10, v10
	v_mul_f32_e32 v10, 0x3fb8aa3b, v10
	v_exp_f32_e32 v10, v10
	v_exp_f32_e32 v12, v12
	v_sub_f32_e32 v10, 1.0, v10
	v_max_f32_e32 v10, 0, v10
	v_cmp_gt_f32_e32 vcc, s31, v10
	v_mul_f32_e32 v14, 0x4f800000, v10
	ds_write_b32 v37, v12 offset:54272
	v_cndmask_b32_e32 v10, v10, v14, vcc
	v_sqrt_f32_e32 v14, v10
	s_nop 0
	v_add_u32_e32 v15, -1, v14
	v_fma_f32 v16, -v15, v14, v10
	v_cmp_ge_f32_e64 s[38:39], 0, v16
	v_add_u32_e32 v16, 1, v14
	s_nop 0
	v_cndmask_b32_e64 v15, v14, v15, s[38:39]
	v_fma_f32 v14, -v16, v14, v10
	v_cmp_lt_f32_e64 s[38:39], 0, v14
	s_nop 1
	v_cndmask_b32_e64 v14, v15, v16, s[38:39]
	ds_read_u16 v16, v31 offset:640
	v_mul_f32_e32 v15, 0x37800000, v14
	v_cndmask_b32_e32 v14, v14, v15, vcc
	v_fma_f32 v15, v39, v46, v0
	v_cmp_class_f32_e32 vcc, v10, v56
	v_fmac_f32_e32 v15, v40, v47
	v_fmac_f32_e32 v15, v42, v44
	v_cndmask_b32_e32 v10, v14, v10, vcc
	s_waitcnt lgkmcnt(0)
; __device__ __forceinline__ float bf2f(bf16_t b) { return __uint_as_float(((unsigned)b) << 16); }
; __device__ __forceinline__ float sigmoidf_(float x) { return frcp(1.0f + fexp2(-x * LOG2E)); }
; template <int APPLY>
; __device__ void lru_item(PP p, int l, int bb, int ck, int nb, unsigned epoch) {
;     ...
;     bf16x8 a[2];
; #pragma unroll
;     for (int ks = 0; ks < 2; ++ks) a[ks] = *(const bf16x8*)(xcs + (wid * 16 + fr) * 72 + ks * 32 + fq * 8);
; #pragma unroll
;     for (int nk = 0; nk < 4; ++nk) {
;       f32x4 ra = f32x4{0.f, 0.f, 0.f, 0.f}, ia = f32x4{0.f, 0.f, 0.f, 0.f};
; #pragma unroll
;       for (int ks = 0; ks < 2; ++ks) {
;         bf16x8 ba = *(const bf16x8*)(wta + (nk * 16 + fr) * 72 + ks * 32 + fq * 8);
;         bf16x8 bx = *(const bf16x8*)(wtx + (nk * 16 + fr) * 72 + ks * 32 + fq * 8);
;         ra = __builtin_amdgcn_mfma_f32_16x16x32_bf16(a[ks], ba, ra, 0, 0, 0);
;         ia = __builtin_amdgcn_mfma_f32_16x16x32_bf16(a[ks], bx, ia, 0, 0, 0);
;       }
;       const int ch = nk * 16 + fr, gch = nb * 64 + ch;
;       const float ba_ = p->lru_b_a[l * 512 + gch], bx_ = p->lru_b_x[l * 512 + gch];
;       const float sp = log1pf(__expf(-p->lru_lambda[l * 512 + gch]));
;       const float* cw = p->conv_w + (long)l * 4 * 512 + gch;
;       const float w0 = cw[0], w1 = cw[512], w2 = cw[1024], w3 = cw[1536], cb = p->conv_b[l * 512 + gch];
; #pragma unroll
;       for (int reg = 0; reg < 4; ++reg) {
;         const int tok = wid * 16 + 4 * fq + reg;
;         const float r = sigmoidf_(ra[reg] + ba_), ig = sigmoidf_(ia[reg] + bx_);
;         const float log_a = -8.0f * r * sp;
;         const float av = __expf(log_a);
;         const float mult = sqrtf(fmaxf(1.0f - __expf(2.0f * log_a), 0.f));
;         const float xc = cb + w0 * bf2f(cxs[(tok + 0) * 64 + ch]) + w1 * bf2f(cxs[(tok + 1) * 64 + ch]) +
;                          w2 * bf2f(cxs[(tok + 2) * 64 + ch]) + w3 * bf2f(cxs[(tok + 3) * 64 + ch]);
;         as_[tok * 64 + ch] = av;
;         bs_[tok * 64 + ch] = mult * ig * xc;
;       }
	v_lshlrev_b32_e32 v16, 16, v16
	v_or_b32_e32 v14, v32, v30
	v_fmac_f32_e32 v15, v41, v16
	v_mul_f32_e32 v10, v11, v10
	v_mul_f32_e32 v10, v15, v10
	v_lshl_add_u32 v11, v14, 2, s4
	ds_write_b32 v11, v10
	v_add_f32_e32 v10, v17, v29
	v_mul_f32_e32 v10, 0xbfb8aa3b, v10
	v_exp_f32_e32 v10, v10
	v_add_f32_e32 v11, v13, v28
	v_mul_f32_e32 v11, 0xbfb8aa3b, v11
	v_exp_f32_e32 v11, v11
	v_add_f32_e32 v10, 1.0, v10
	v_rcp_f32_e32 v10, v10
	v_add_f32_e32 v11, 1.0, v11
	v_rcp_f32_e32 v11, v11
	v_mul_f32_e32 v10, 0xc1000000, v10
	v_mul_f32_e32 v10, v10, v33
	v_mul_f32_e32 v12, 0x3fb8aa3b, v10
	v_add_f32_e32 v10, v10, v10
	v_mul_f32_e32 v10, 0x3fb8aa3b, v10
	v_exp_f32_e32 v10, v10
	v_exp_f32_e32 v12, v12
	v_or_b32_e32 v33, 0xc0, v38
	v_sub_f32_e32 v10, 1.0, v10
	v_max_f32_e32 v10, 0, v10
	v_cmp_gt_f32_e32 vcc, s31, v10
	v_mul_f32_e32 v13, 0x4f800000, v10
	ds_write_b32 v37, v12 offset:54528
	v_cndmask_b32_e32 v10, v10, v13, vcc
	v_sqrt_f32_e32 v13, v10
	s_nop 0
	v_add_u32_e32 v14, -1, v13
	v_fma_f32 v15, -v14, v13, v10
	v_cmp_ge_f32_e64 s[38:39], 0, v15
	v_add_u32_e32 v15, 1, v13
	s_nop 0
	v_cndmask_b32_e64 v14, v13, v14, s[38:39]
	v_fma_f32 v13, -v15, v13, v10
	v_cmp_lt_f32_e64 s[38:39], 0, v13
	s_nop 1
	v_cndmask_b32_e64 v13, v14, v15, s[38:39]
	v_mul_f32_e32 v14, 0x37800000, v13
	v_cndmask_b32_e32 v13, v13, v14, vcc
	ds_read_u16 v14, v31 offset:384
	v_cmp_class_f32_e32 vcc, v10, v56
	s_waitcnt lgkmcnt(0)
	v_lshlrev_b32_e32 v14, 16, v14
	v_fmac_f32_e32 v0, v39, v14
	ds_read_u16 v14, v31 offset:768
	v_fmac_f32_e32 v0, v40, v44
	v_cndmask_b32_e32 v10, v13, v10, vcc
	v_fmac_f32_e32 v0, v42, v16
	v_or_b32_e32 v13, v33, v30
	s_waitcnt lgkmcnt(0)
	v_lshlrev_b32_e32 v14, 16, v14
	v_fmac_f32_e32 v0, v41, v14
	v_mul_f32_e32 v10, v11, v10
	v_mul_f32_e32 v0, v0, v10
	v_lshl_add_u32 v10, v13, 2, s4
	v_or_b32_e32 v40, 16, v30
	ds_write_b32 v10, v0
	v_mul_u32_u24_e32 v0, 0x48, v40
	v_lshl_add_u32 v0, v0, 1, v34
	ds_read_b128 v[10:13], v0 offset:35328
	ds_read_b128 v[14:17], v0 offset:44544
	s_waitcnt lgkmcnt(0)
	v_mfma_f32_16x16x32_bf16 v[42:45], v[6:9], v[14:17], 0
	ds_read_b128 v[14:17], v0 offset:35392
	ds_read_b128 v[46:49], v0 offset:44608
	v_add_u32_e32 v0, s89, v30
	v_add_lshl_u32 v39, v0, s60, 2
	v_mfma_f32_16x16x32_bf16 v[10:13], v[6:9], v[10:13], 0
	v_lshlrev_b32_e32 v0, 2, v0
	s_waitcnt lgkmcnt(1)
	v_mfma_f32_16x16x32_bf16 v[14:17], v[2:5], v[14:17], v[10:13]
	s_waitcnt lgkmcnt(0)
	v_mfma_f32_16x16x32_bf16 v[10:13], v[2:5], v[46:49], v[42:45]
	s_nop 2
	global_load_dword v42, v39, s[56:57] offset:64
	global_load_dword v41, v39, s[48:49] offset:64
	global_load_dword v28, v39, s[50:51] offset:64
	s_waitcnt vmcnt(2)
	v_add_f32_e32 v14, v14, v42
	v_mul_f32_e32 v14, 0xbfb8aa3b, v14
	s_waitcnt vmcnt(0)
	v_exp_f32_e32 v14, v14
	v_add_f32_e32 v10, v10, v41
	v_mul_f32_e32 v10, 0xbfb8aa3b, v10
	v_add_f32_e32 v14, 1.0, v14
	global_load_dword v44, v0, s[40:41] offset:64
	global_load_dword v45, v0, s[40:41] offset:2112
	v_rcp_f32_e32 v14, v14
	v_exp_f32_e32 v10, v10
	v_mul_f32_e32 v14, 0xc1000000, v14
	v_add_f32_e32 v10, 1.0, v10
	v_mov_b32_e32 v48, v28
	v_lshl_add_u64 v[28:29], s[40:41], 0, v[0:1]
	v_add_co_u32_e32 v28, vcc, s6, v28
	v_mul_f32_e32 v49, v14, v48
	s_nop 0
	v_addc_co_u32_e32 v29, vcc, 0, v29, vcc
	global_load_dword v47, v[28:29], off offset:64
	global_load_dword v46, v[28:29], off offset:2112
	global_load_dword v43, v39, s[46:47] offset:64
	v_mul_f32_e32 v14, 0x3fb8aa3b, v49
	v_add_f32_e32 v49, v49, v49
	v_mul_f32_e32 v49, 0x3fb8aa3b, v49
	v_exp_f32_e32 v49, v49
	ds_read_u16 v53, v31 offset:288
	ds_read_u16 v54, v31 offset:416
	v_rcp_f32_e32 v10, v10
	v_sub_f32_e32 v49, 1.0, v49
	v_max_f32_e32 v49, 0, v49
	v_cmp_gt_f32_e32 vcc, s31, v49
	v_mul_f32_e32 v50, 0x4f800000, v49
	v_exp_f32_e32 v14, v14
	v_cndmask_b32_e32 v49, v49, v50, vcc
	v_sqrt_f32_e32 v50, v49
	s_waitcnt lgkmcnt(1)
	v_lshlrev_b32_e32 v53, 16, v53
	s_waitcnt lgkmcnt(0)
	v_lshlrev_b32_e32 v54, 16, v54
	ds_write_b32 v37, v14 offset:53824
	v_add_u32_e32 v51, -1, v50
	v_fma_f32 v52, -v51, v50, v49
	v_cmp_ge_f32_e64 s[38:39], 0, v52
	v_add_u32_e32 v52, 1, v50
	v_add_f32_e32 v11, v11, v41
	v_cndmask_b32_e64 v51, v50, v51, s[38:39]
	v_fma_f32 v50, -v52, v50, v49
	v_cmp_lt_f32_e64 s[38:39], 0, v50
	v_mul_f32_e32 v11, 0xbfb8aa3b, v11
	v_exp_f32_e32 v11, v11
	v_cndmask_b32_e64 v50, v51, v52, s[38:39]
	v_mul_f32_e32 v51, 0x37800000, v50
	v_cndmask_b32_e32 v50, v50, v51, vcc
	ds_read_u16 v51, v31 offset:32
	ds_read_u16 v52, v31 offset:160
	v_cmp_class_f32_e32 vcc, v49, v56
	v_add_f32_e32 v11, 1.0, v11
	v_rcp_f32_e32 v11, v11
	s_waitcnt lgkmcnt(1)
	v_lshlrev_b32_e32 v51, 16, v51
	s_waitcnt lgkmcnt(0)
	v_lshlrev_b32_e32 v52, 16, v52
	v_cndmask_b32_e32 v50, v50, v49, vcc
	v_or_b32_e32 v49, v38, v40
	v_mul_f32_e32 v10, v10, v50
	v_lshlrev_b32_e32 v14, 2, v49
	v_add_u32_e32 v49, s4, v14
	v_add_u32_e32 v14, 0, v14
	s_waitcnt vmcnt(0)
	v_fma_f32 v51, v44, v51, v43
	v_fmac_f32_e32 v51, v45, v52
	v_fmac_f32_e32 v51, v47, v53
	v_fmac_f32_e32 v51, v46, v54
	v_mul_f32_e32 v10, v51, v10
	ds_write_b32 v49, v10
	v_add_f32_e32 v10, v15, v42
	v_mul_f32_e32 v10, 0xbfb8aa3b, v10
	v_exp_f32_e32 v10, v10
	s_nop 0
	v_add_f32_e32 v10, 1.0, v10
	v_rcp_f32_e32 v10, v10
	s_nop 0
	v_mul_f32_e32 v10, 0xc1000000, v10
	v_mul_f32_e32 v10, v10, v48
	v_mul_f32_e32 v15, 0x3fb8aa3b, v10
	v_add_f32_e32 v10, v10, v10
	v_mul_f32_e32 v10, 0x3fb8aa3b, v10
	v_exp_f32_e32 v10, v10
	v_exp_f32_e32 v15, v15
	v_sub_f32_e32 v10, 1.0, v10
	v_max_f32_e32 v10, 0, v10
	v_cmp_gt_f32_e32 vcc, s31, v10
	v_mul_f32_e32 v49, 0x4f800000, v10
	ds_write_b32 v14, v15 offset:54016
	v_cndmask_b32_e32 v10, v10, v49, vcc
	v_sqrt_f32_e32 v49, v10
	s_nop 0
	v_add_u32_e32 v50, -1, v49
	v_fma_f32 v51, -v50, v49, v10
	v_cmp_ge_f32_e64 s[38:39], 0, v51
	v_add_u32_e32 v51, 1, v49
	s_nop 0
	v_cndmask_b32_e64 v50, v49, v50, s[38:39]
	v_fma_f32 v49, -v51, v49, v10
	v_cmp_lt_f32_e64 s[38:39], 0, v49
	s_nop 1
	v_cndmask_b32_e64 v49, v50, v51, s[38:39]
	v_fma_f32 v51, v44, v52, v43
	ds_read_u16 v52, v31 offset:544
	v_mul_f32_e32 v50, 0x37800000, v49
	v_cndmask_b32_e32 v49, v49, v50, vcc
	v_cmp_class_f32_e32 vcc, v10, v56
	v_fmac_f32_e32 v51, v45, v53
	v_fmac_f32_e32 v51, v47, v54
	v_cndmask_b32_e32 v10, v49, v10, vcc
	s_waitcnt lgkmcnt(0)
; __device__ __forceinline__ float bf2f(bf16_t b) { return __uint_as_float(((unsigned)b) << 16); }
; __device__ __forceinline__ float sigmoidf_(float x) { return frcp(1.0f + fexp2(-x * LOG2E)); }
; template <int APPLY>
; __device__ void lru_item(PP p, int l, int bb, int ck, int nb, unsigned epoch) {
;     ...
;     bf16x8 a[2];
; #pragma unroll
;     for (int ks = 0; ks < 2; ++ks) a[ks] = *(const bf16x8*)(xcs + (wid * 16 + fr) * 72 + ks * 32 + fq * 8);
; #pragma unroll
;     for (int nk = 0; nk < 4; ++nk) {
;       f32x4 ra = f32x4{0.f, 0.f, 0.f, 0.f}, ia = f32x4{0.f, 0.f, 0.f, 0.f};
; #pragma unroll
;       for (int ks = 0; ks < 2; ++ks) {
;         bf16x8 ba = *(const bf16x8*)(wta + (nk * 16 + fr) * 72 + ks * 32 + fq * 8);
;         bf16x8 bx = *(const bf16x8*)(wtx + (nk * 16 + fr) * 72 + ks * 32 + fq * 8);
;         ra = __builtin_amdgcn_mfma_f32_16x16x32_bf16(a[ks], ba, ra, 0, 0, 0);
;         ia = __builtin_amdgcn_mfma_f32_16x16x32_bf16(a[ks], bx, ia, 0, 0, 0);
;       }
;       const int ch = nk * 16 + fr, gch = nb * 64 + ch;
;       const float ba_ = p->lru_b_a[l * 512 + gch], bx_ = p->lru_b_x[l * 512 + gch];
;       const float sp = log1pf(__expf(-p->lru_lambda[l * 512 + gch]));
;       const float* cw = p->conv_w + (long)l * 4 * 512 + gch;
;       const float w0 = cw[0], w1 = cw[512], w2 = cw[1024], w3 = cw[1536], cb = p->conv_b[l * 512 + gch];
; #pragma unroll
;       for (int reg = 0; reg < 4; ++reg) {
;         const int tok = wid * 16 + 4 * fq + reg;
;         const float r = sigmoidf_(ra[reg] + ba_), ig = sigmoidf_(ia[reg] + bx_);
;         const float log_a = -8.0f * r * sp;
;         const float av = __expf(log_a);
;         const float mult = sqrtf(fmaxf(1.0f - __expf(2.0f * log_a), 0.f));
;         const float xc = cb + w0 * bf2f(cxs[(tok + 0) * 64 + ch]) + w1 * bf2f(cxs[(tok + 1) * 64 + ch]) +
;                          w2 * bf2f(cxs[(tok + 2) * 64 + ch]) + w3 * bf2f(cxs[(tok + 3) * 64 + ch]);
;         as_[tok * 64 + ch] = av;
;         bs_[tok * 64 + ch] = mult * ig * xc;
;       }
	v_lshlrev_b32_e32 v52, 16, v52
	v_or_b32_e32 v49, v36, v40
	v_fmac_f32_e32 v51, v46, v52
	v_mul_f32_e32 v10, v11, v10
	v_mul_f32_e32 v10, v51, v10
	v_lshl_add_u32 v11, v49, 2, s4
	ds_write_b32 v11, v10
	v_add_f32_e32 v10, v16, v42
	v_mul_f32_e32 v10, 0xbfb8aa3b, v10
	v_exp_f32_e32 v10, v10
	v_add_f32_e32 v11, v12, v41
	v_mul_f32_e32 v11, 0xbfb8aa3b, v11
	v_exp_f32_e32 v11, v11
	v_add_f32_e32 v10, 1.0, v10
	v_rcp_f32_e32 v10, v10
	v_lshl_add_u32 v50, v40, 1, v35
	v_add_f32_e32 v11, 1.0, v11
	v_rcp_f32_e32 v11, v11
	v_mul_f32_e32 v10, 0xc1000000, v10
	v_mul_f32_e32 v10, v10, v48
	v_mul_f32_e32 v12, 0x3fb8aa3b, v10
	v_add_f32_e32 v10, v10, v10
	v_mul_f32_e32 v10, 0x3fb8aa3b, v10
	v_exp_f32_e32 v10, v10
	v_exp_f32_e32 v12, v12
	v_sub_f32_e32 v10, 1.0, v10
	v_max_f32_e32 v10, 0, v10
	v_cmp_gt_f32_e32 vcc, s31, v10
	v_mul_f32_e32 v15, 0x4f800000, v10
	ds_write_b32 v14, v12 offset:54272
	v_cndmask_b32_e32 v10, v10, v15, vcc
	v_sqrt_f32_e32 v15, v10
	s_nop 0
	v_add_u32_e32 v16, -1, v15
	v_fma_f32 v49, -v16, v15, v10
	v_cmp_ge_f32_e64 s[38:39], 0, v49
	v_add_u32_e32 v49, 1, v15
	s_nop 0
	v_cndmask_b32_e64 v16, v15, v16, s[38:39]
	v_fma_f32 v15, -v49, v15, v10
	v_cmp_lt_f32_e64 s[38:39], 0, v15
	s_nop 1
	v_cndmask_b32_e64 v15, v16, v49, s[38:39]
	ds_read_u16 v49, v31 offset:672
	v_mul_f32_e32 v16, 0x37800000, v15
	v_cndmask_b32_e32 v15, v15, v16, vcc
	v_fma_f32 v16, v44, v53, v43
	v_cmp_class_f32_e32 vcc, v10, v56
	v_fmac_f32_e32 v16, v45, v54
	v_fmac_f32_e32 v16, v47, v52
	v_cndmask_b32_e32 v10, v15, v10, vcc
	s_waitcnt lgkmcnt(0)
	v_lshlrev_b32_e32 v49, 16, v49
	v_or_b32_e32 v15, v32, v40
	v_fmac_f32_e32 v16, v46, v49
	v_mul_f32_e32 v10, v11, v10
	v_mul_f32_e32 v10, v16, v10
	v_lshl_add_u32 v11, v15, 2, s4
	ds_write_b32 v11, v10
	v_add_f32_e32 v10, v17, v42
	v_mul_f32_e32 v10, 0xbfb8aa3b, v10
	v_exp_f32_e32 v10, v10
	v_add_f32_e32 v11, v13, v41
	v_mul_f32_e32 v11, 0xbfb8aa3b, v11
	v_exp_f32_e32 v11, v11
	v_add_f32_e32 v10, 1.0, v10
	v_rcp_f32_e32 v10, v10
	v_add_f32_e32 v11, 1.0, v11
	v_rcp_f32_e32 v11, v11
	v_mul_f32_e32 v10, 0xc1000000, v10
	v_mul_f32_e32 v10, v10, v48
	v_mul_f32_e32 v12, 0x3fb8aa3b, v10
	v_add_f32_e32 v10, v10, v10
	v_mul_f32_e32 v10, 0x3fb8aa3b, v10
	v_exp_f32_e32 v10, v10
	v_exp_f32_e32 v12, v12
	v_sub_f32_e32 v10, 1.0, v10
	v_max_f32_e32 v10, 0, v10
	v_cmp_gt_f32_e32 vcc, s31, v10
	v_mul_f32_e32 v13, 0x4f800000, v10
	ds_write_b32 v14, v12 offset:54528
	v_cndmask_b32_e32 v10, v10, v13, vcc
	v_sqrt_f32_e32 v13, v10
	s_nop 0
	v_add_u32_e32 v15, -1, v13
	v_fma_f32 v16, -v15, v13, v10
	v_cmp_ge_f32_e64 s[38:39], 0, v16
	v_add_u32_e32 v16, 1, v13
	s_nop 0
	v_cndmask_b32_e64 v15, v13, v15, s[38:39]
	v_fma_f32 v13, -v16, v13, v10
	v_cmp_lt_f32_e64 s[38:39], 0, v13
	s_nop 1
	v_cndmask_b32_e64 v13, v15, v16, s[38:39]
	v_mul_f32_e32 v15, 0x37800000, v13
	v_cndmask_b32_e32 v13, v13, v15, vcc
	ds_read_u16 v15, v50 offset:384
	v_cmp_class_f32_e32 vcc, v10, v56
	s_waitcnt lgkmcnt(0)
	v_lshlrev_b32_e32 v15, 16, v15
	v_fmac_f32_e32 v43, v44, v15
	ds_read_u16 v15, v31 offset:800
	v_fmac_f32_e32 v43, v45, v52
	v_cndmask_b32_e32 v10, v13, v10, vcc
	v_fmac_f32_e32 v43, v47, v49
	v_or_b32_e32 v13, v33, v40
	s_waitcnt lgkmcnt(0)
	v_lshlrev_b32_e32 v15, 16, v15
	v_fmac_f32_e32 v43, v46, v15
	v_mul_f32_e32 v10, v11, v10
	v_mul_f32_e32 v10, v43, v10
	v_lshl_add_u32 v11, v13, 2, s4
	v_or_b32_e32 v40, 32, v30
	ds_write_b32 v11, v10
	v_mul_u32_u24_e32 v10, 0x48, v40
	v_lshl_add_u32 v41, v10, 1, v34
	ds_read_b128 v[10:13], v41 offset:35328
	ds_read_b128 v[14:17], v41 offset:44544
	s_waitcnt lgkmcnt(0)
	v_mfma_f32_16x16x32_bf16 v[42:45], v[6:9], v[14:17], 0
	ds_read_b128 v[14:17], v41 offset:35392
	ds_read_b128 v[46:49], v41 offset:44608
	v_mfma_f32_16x16x32_bf16 v[10:13], v[6:9], v[10:13], 0
	s_waitcnt lgkmcnt(1)
	v_mfma_f32_16x16x32_bf16 v[14:17], v[2:5], v[14:17], v[10:13]
	s_waitcnt lgkmcnt(0)
	v_mfma_f32_16x16x32_bf16 v[10:13], v[2:5], v[46:49], v[42:45]
	s_nop 2
	global_load_dword v42, v39, s[56:57] offset:128
	global_load_dword v41, v39, s[48:49] offset:128
	global_load_dword v43, v39, s[50:51] offset:128
	s_waitcnt vmcnt(2)
	v_add_f32_e32 v14, v14, v42
	v_mul_f32_e32 v14, 0xbfb8aa3b, v14
	s_waitcnt vmcnt(0)
	v_exp_f32_e32 v14, v14
	v_add_f32_e32 v10, v10, v41
	v_mul_f32_e32 v10, 0xbfb8aa3b, v10
	v_add_f32_e32 v14, 1.0, v14
	v_rcp_f32_e32 v14, v14
	v_exp_f32_e32 v10, v10
	v_mul_f32_e32 v14, 0xc1000000, v14
	v_add_f32_e32 v10, 1.0, v10
	v_rcp_f32_e32 v10, v10
	v_add_f32_e32 v11, v11, v41
	v_mov_b32_e32 v48, v43
	global_load_dword v45, v0, s[40:41] offset:128
	global_load_dword v46, v0, s[40:41] offset:2176
	global_load_dword v47, v[28:29], off offset:128
	global_load_dword v44, v[28:29], off offset:2176
	global_load_dword v43, v39, s[46:47] offset:128
	v_mul_f32_e32 v49, v14, v48
	v_mul_f32_e32 v14, 0x3fb8aa3b, v49
	v_add_f32_e32 v49, v49, v49
	v_mul_f32_e32 v49, 0x3fb8aa3b, v49
	v_exp_f32_e32 v49, v49
	ds_read_u16 v53, v31 offset:320
	ds_read_u16 v54, v31 offset:448
	v_exp_f32_e32 v14, v14
	v_sub_f32_e32 v49, 1.0, v49
	v_max_f32_e32 v49, 0, v49
	v_cmp_gt_f32_e32 vcc, s31, v49
	v_mul_f32_e32 v50, 0x4f800000, v49
	s_waitcnt lgkmcnt(1)
	v_lshlrev_b32_e32 v53, 16, v53
	v_cndmask_b32_e32 v49, v49, v50, vcc
	v_sqrt_f32_e32 v50, v49
	s_waitcnt lgkmcnt(0)
	v_lshlrev_b32_e32 v54, 16, v54
	ds_write_b32 v37, v14 offset:53888
	v_mul_f32_e32 v11, 0xbfb8aa3b, v11
	v_add_u32_e32 v51, -1, v50
	v_fma_f32 v52, -v51, v50, v49
	v_cmp_ge_f32_e64 s[38:39], 0, v52
	v_add_u32_e32 v52, 1, v50
	v_exp_f32_e32 v11, v11
	v_cndmask_b32_e64 v51, v50, v51, s[38:39]
	v_fma_f32 v50, -v52, v50, v49
	v_cmp_lt_f32_e64 s[38:39], 0, v50
	v_add_f32_e32 v11, 1.0, v11
	v_rcp_f32_e32 v11, v11
	v_cndmask_b32_e64 v50, v51, v52, s[38:39]
	v_mul_f32_e32 v51, 0x37800000, v50
	v_cndmask_b32_e32 v50, v50, v51, vcc
	ds_read_u16 v51, v31 offset:64
	ds_read_u16 v52, v31 offset:192
	v_cmp_class_f32_e32 vcc, v49, v56
	s_waitcnt lgkmcnt(1)
; __device__ __forceinline__ float bf2f(bf16_t b) { return __uint_as_float(((unsigned)b) << 16); }
; __device__ __forceinline__ float sigmoidf_(float x) { return frcp(1.0f + fexp2(-x * LOG2E)); }
; template <int APPLY>
; __device__ void lru_item(PP p, int l, int bb, int ck, int nb, unsigned epoch) {
;     ...
;     bf16x8 a[2];
; #pragma unroll
;     for (int ks = 0; ks < 2; ++ks) a[ks] = *(const bf16x8*)(xcs + (wid * 16 + fr) * 72 + ks * 32 + fq * 8);
; #pragma unroll
;     for (int nk = 0; nk < 4; ++nk) {
;       f32x4 ra = f32x4{0.f, 0.f, 0.f, 0.f}, ia = f32x4{0.f, 0.f, 0.f, 0.f};
; #pragma unroll
;       for (int ks = 0; ks < 2; ++ks) {
;         bf16x8 ba = *(const bf16x8*)(wta + (nk * 16 + fr) * 72 + ks * 32 + fq * 8);
;         bf16x8 bx = *(const bf16x8*)(wtx + (nk * 16 + fr) * 72 + ks * 32 + fq * 8);
;         ra = __builtin_amdgcn_mfma_f32_16x16x32_bf16(a[ks], ba, ra, 0, 0, 0);
;         ia = __builtin_amdgcn_mfma_f32_16x16x32_bf16(a[ks], bx, ia, 0, 0, 0);
;       }
;       const int ch = nk * 16 + fr, gch = nb * 64 + ch;
;       const float ba_ = p->lru_b_a[l * 512 + gch], bx_ = p->lru_b_x[l * 512 + gch];
;       const float sp = log1pf(__expf(-p->lru_lambda[l * 512 + gch]));
;       const float* cw = p->conv_w + (long)l * 4 * 512 + gch;
;       const float w0 = cw[0], w1 = cw[512], w2 = cw[1024], w3 = cw[1536], cb = p->conv_b[l * 512 + gch];
; #pragma unroll
;       for (int reg = 0; reg < 4; ++reg) {
;         const int tok = wid * 16 + 4 * fq + reg;
;         const float r = sigmoidf_(ra[reg] + ba_), ig = sigmoidf_(ia[reg] + bx_);
;         const float log_a = -8.0f * r * sp;
;         const float av = __expf(log_a);
;         const float mult = sqrtf(fmaxf(1.0f - __expf(2.0f * log_a), 0.f));
;         const float xc = cb + w0 * bf2f(cxs[(tok + 0) * 64 + ch]) + w1 * bf2f(cxs[(tok + 1) * 64 + ch]) +
;                          w2 * bf2f(cxs[(tok + 2) * 64 + ch]) + w3 * bf2f(cxs[(tok + 3) * 64 + ch]);
;         as_[tok * 64 + ch] = av;
;         bs_[tok * 64 + ch] = mult * ig * xc;
;       }
	v_lshlrev_b32_e32 v51, 16, v51
	s_waitcnt lgkmcnt(0)
	v_lshlrev_b32_e32 v52, 16, v52
	v_cndmask_b32_e32 v50, v50, v49, vcc
	v_or_b32_e32 v49, v38, v40
	v_mul_f32_e32 v10, v10, v50
	v_lshlrev_b32_e32 v14, 2, v49
	v_add_u32_e32 v49, s4, v14
	v_add_u32_e32 v14, 0, v14
	s_waitcnt vmcnt(0)
	v_fma_f32 v51, v45, v51, v43
	v_fmac_f32_e32 v51, v46, v52
	v_fmac_f32_e32 v51, v47, v53
	v_fmac_f32_e32 v51, v44, v54
	v_mul_f32_e32 v10, v51, v10
	ds_write_b32 v49, v10
	v_add_f32_e32 v10, v15, v42
	v_mul_f32_e32 v10, 0xbfb8aa3b, v10
	v_exp_f32_e32 v10, v10
	s_nop 0
	v_add_f32_e32 v10, 1.0, v10
	v_rcp_f32_e32 v10, v10
	s_nop 0
	v_mul_f32_e32 v10, 0xc1000000, v10
	v_mul_f32_e32 v10, v10, v48
	v_mul_f32_e32 v15, 0x3fb8aa3b, v10
	v_add_f32_e32 v10, v10, v10
	v_mul_f32_e32 v10, 0x3fb8aa3b, v10
	v_exp_f32_e32 v10, v10
	v_exp_f32_e32 v15, v15
	v_sub_f32_e32 v10, 1.0, v10
	v_max_f32_e32 v10, 0, v10
	v_cmp_gt_f32_e32 vcc, s31, v10
	v_mul_f32_e32 v49, 0x4f800000, v10
	ds_write_b32 v14, v15 offset:54016
	v_cndmask_b32_e32 v10, v10, v49, vcc
	v_sqrt_f32_e32 v49, v10
	s_nop 0
	v_add_u32_e32 v50, -1, v49
	v_fma_f32 v51, -v50, v49, v10
	v_cmp_ge_f32_e64 s[38:39], 0, v51
	v_add_u32_e32 v51, 1, v49
	s_nop 0
	v_cndmask_b32_e64 v50, v49, v50, s[38:39]
	v_fma_f32 v49, -v51, v49, v10
	v_cmp_lt_f32_e64 s[38:39], 0, v49
	s_nop 1
	v_cndmask_b32_e64 v49, v50, v51, s[38:39]
	v_fma_f32 v51, v45, v52, v43
	ds_read_u16 v52, v31 offset:576
	v_mul_f32_e32 v50, 0x37800000, v49
	v_cndmask_b32_e32 v49, v49, v50, vcc
	v_cmp_class_f32_e32 vcc, v10, v56
	v_fmac_f32_e32 v51, v46, v53
	v_fmac_f32_e32 v51, v47, v54
	v_cndmask_b32_e32 v10, v49, v10, vcc
	s_waitcnt lgkmcnt(0)
	v_lshlrev_b32_e32 v52, 16, v52
	v_or_b32_e32 v49, v36, v40
	v_fmac_f32_e32 v51, v44, v52
	v_mul_f32_e32 v10, v11, v10
	v_mul_f32_e32 v10, v51, v10
	v_lshl_add_u32 v11, v49, 2, s4
	ds_write_b32 v11, v10
	v_add_f32_e32 v10, v16, v42
	v_mul_f32_e32 v10, 0xbfb8aa3b, v10
	v_exp_f32_e32 v10, v10
	v_add_f32_e32 v11, v12, v41
	v_mul_f32_e32 v11, 0xbfb8aa3b, v11
	v_exp_f32_e32 v11, v11
	v_add_f32_e32 v10, 1.0, v10
	v_rcp_f32_e32 v10, v10
	v_lshl_add_u32 v50, v40, 1, v35
	v_add_f32_e32 v11, 1.0, v11
	v_rcp_f32_e32 v11, v11
	v_mul_f32_e32 v10, 0xc1000000, v10
	v_mul_f32_e32 v10, v10, v48
	v_mul_f32_e32 v12, 0x3fb8aa3b, v10
	v_add_f32_e32 v10, v10, v10
	v_mul_f32_e32 v10, 0x3fb8aa3b, v10
	v_exp_f32_e32 v10, v10
	v_exp_f32_e32 v12, v12
	v_sub_f32_e32 v10, 1.0, v10
	v_max_f32_e32 v10, 0, v10
	v_cmp_gt_f32_e32 vcc, s31, v10
	v_mul_f32_e32 v15, 0x4f800000, v10
	ds_write_b32 v14, v12 offset:54272
	v_cndmask_b32_e32 v10, v10, v15, vcc
	v_sqrt_f32_e32 v15, v10
	s_nop 0
	v_add_u32_e32 v16, -1, v15
	v_fma_f32 v49, -v16, v15, v10
	v_cmp_ge_f32_e64 s[38:39], 0, v49
	v_add_u32_e32 v49, 1, v15
	s_nop 0
	v_cndmask_b32_e64 v16, v15, v16, s[38:39]
	v_fma_f32 v15, -v49, v15, v10
	v_cmp_lt_f32_e64 s[38:39], 0, v15
	s_nop 1
	v_cndmask_b32_e64 v15, v16, v49, s[38:39]
	ds_read_u16 v49, v31 offset:704
	v_mul_f32_e32 v16, 0x37800000, v15
	v_cndmask_b32_e32 v15, v15, v16, vcc
	v_fma_f32 v16, v45, v53, v43
	v_cmp_class_f32_e32 vcc, v10, v56
	v_fmac_f32_e32 v16, v46, v54
	v_fmac_f32_e32 v16, v47, v52
	v_cndmask_b32_e32 v10, v15, v10, vcc
	s_waitcnt lgkmcnt(0)
	v_lshlrev_b32_e32 v49, 16, v49
	v_or_b32_e32 v15, v32, v40
	v_fmac_f32_e32 v16, v44, v49
	v_mul_f32_e32 v10, v11, v10
	v_mul_f32_e32 v10, v16, v10
	v_lshl_add_u32 v11, v15, 2, s4
	ds_write_b32 v11, v10
	v_add_f32_e32 v10, v17, v42
	v_mul_f32_e32 v10, 0xbfb8aa3b, v10
	v_exp_f32_e32 v10, v10
	v_add_f32_e32 v11, v13, v41
	v_mul_f32_e32 v11, 0xbfb8aa3b, v11
	v_exp_f32_e32 v11, v11
	v_add_f32_e32 v10, 1.0, v10
	v_rcp_f32_e32 v10, v10
	v_add_f32_e32 v11, 1.0, v11
	v_rcp_f32_e32 v11, v11
	v_mul_f32_e32 v10, 0xc1000000, v10
	v_mul_f32_e32 v10, v10, v48
	v_mul_f32_e32 v12, 0x3fb8aa3b, v10
	v_add_f32_e32 v10, v10, v10
	v_mul_f32_e32 v10, 0x3fb8aa3b, v10
	v_exp_f32_e32 v10, v10
	v_exp_f32_e32 v12, v12
	v_sub_f32_e32 v10, 1.0, v10
	v_max_f32_e32 v10, 0, v10
	v_cmp_gt_f32_e32 vcc, s31, v10
	v_mul_f32_e32 v13, 0x4f800000, v10
	ds_write_b32 v14, v12 offset:54528
	v_cndmask_b32_e32 v10, v10, v13, vcc
	v_sqrt_f32_e32 v13, v10
	s_nop 0
	v_add_u32_e32 v15, -1, v13
	v_fma_f32 v16, -v15, v13, v10
	v_cmp_ge_f32_e64 s[38:39], 0, v16
	v_add_u32_e32 v16, 1, v13
	s_nop 0
	v_cndmask_b32_e64 v15, v13, v15, s[38:39]
	v_fma_f32 v13, -v16, v13, v10
	v_cmp_lt_f32_e64 s[38:39], 0, v13
	s_nop 1
	v_cndmask_b32_e64 v13, v15, v16, s[38:39]
	v_mul_f32_e32 v15, 0x37800000, v13
	v_cndmask_b32_e32 v13, v13, v15, vcc
	ds_read_u16 v15, v50 offset:384
	v_cmp_class_f32_e32 vcc, v10, v56
	s_waitcnt lgkmcnt(0)
	v_lshlrev_b32_e32 v15, 16, v15
	v_fmac_f32_e32 v43, v45, v15
	ds_read_u16 v15, v31 offset:832
	v_fmac_f32_e32 v43, v46, v52
	v_cndmask_b32_e32 v10, v13, v10, vcc
	v_fmac_f32_e32 v43, v47, v49
	v_or_b32_e32 v13, v33, v40
	s_waitcnt lgkmcnt(0)
	v_lshlrev_b32_e32 v15, 16, v15
	v_fmac_f32_e32 v43, v44, v15
	v_mul_f32_e32 v10, v11, v10
	v_mul_f32_e32 v10, v43, v10
	v_lshl_add_u32 v11, v13, 2, s4
	ds_write_b32 v11, v10
	v_or_b32_e32 v11, 48, v30
	v_mul_u32_u24_e32 v10, 0x48, v11
	v_lshl_add_u32 v10, v10, 1, v34
	ds_read_b128 v[12:15], v10 offset:35328
	ds_read_b128 v[40:43], v10 offset:44544
	s_waitcnt lgkmcnt(1)
	v_mfma_f32_16x16x32_bf16 v[12:15], v[6:9], v[12:15], 0
	s_waitcnt lgkmcnt(0)
	v_mfma_f32_16x16x32_bf16 v[40:43], v[6:9], v[40:43], 0
	ds_read_b128 v[6:9], v10 offset:35392
	ds_read_b128 v[44:47], v10 offset:44608
	s_waitcnt lgkmcnt(1)
	v_mfma_f32_16x16x32_bf16 v[6:9], v[2:5], v[6:9], v[12:15]
	s_nop 2
	global_load_dword v13, v39, s[56:57] offset:192
	global_load_dword v12, v39, s[48:49] offset:192
	global_load_dword v10, v39, s[50:51] offset:192
	s_waitcnt vmcnt(2)
; __device__ __forceinline__ float bf2f(bf16_t b) { return __uint_as_float(((unsigned)b) << 16); }
; __device__ __forceinline__ float sigmoidf_(float x) { return frcp(1.0f + fexp2(-x * LOG2E)); }
; template <int APPLY>
; __device__ void lru_item(PP p, int l, int bb, int ck, int nb, unsigned epoch) {
;     ...
;     bf16x8 a[2];
; #pragma unroll
;     for (int ks = 0; ks < 2; ++ks) a[ks] = *(const bf16x8*)(xcs + (wid * 16 + fr) * 72 + ks * 32 + fq * 8);
; #pragma unroll
;     for (int nk = 0; nk < 4; ++nk) {
;       f32x4 ra = f32x4{0.f, 0.f, 0.f, 0.f}, ia = f32x4{0.f, 0.f, 0.f, 0.f};
; #pragma unroll
;       for (int ks = 0; ks < 2; ++ks) {
;         bf16x8 ba = *(const bf16x8*)(wta + (nk * 16 + fr) * 72 + ks * 32 + fq * 8);
;         bf16x8 bx = *(const bf16x8*)(wtx + (nk * 16 + fr) * 72 + ks * 32 + fq * 8);
;         ra = __builtin_amdgcn_mfma_f32_16x16x32_bf16(a[ks], ba, ra, 0, 0, 0);
;         ia = __builtin_amdgcn_mfma_f32_16x16x32_bf16(a[ks], bx, ia, 0, 0, 0);
;       }
;       const int ch = nk * 16 + fr, gch = nb * 64 + ch;
;       const float ba_ = p->lru_b_a[l * 512 + gch], bx_ = p->lru_b_x[l * 512 + gch];
;       const float sp = log1pf(__expf(-p->lru_lambda[l * 512 + gch]));
;       const float* cw = p->conv_w + (long)l * 4 * 512 + gch;
;       const float w0 = cw[0], w1 = cw[512], w2 = cw[1024], w3 = cw[1536], cb = p->conv_b[l * 512 + gch];
; #pragma unroll
;       for (int reg = 0; reg < 4; ++reg) {
;         const int tok = wid * 16 + 4 * fq + reg;
;         const float r = sigmoidf_(ra[reg] + ba_), ig = sigmoidf_(ia[reg] + bx_);
;         const float log_a = -8.0f * r * sp;
;         const float av = __expf(log_a);
;         const float mult = sqrtf(fmaxf(1.0f - __expf(2.0f * log_a), 0.f));
;         const float xc = cb + w0 * bf2f(cxs[(tok + 0) * 64 + ch]) + w1 * bf2f(cxs[(tok + 1) * 64 + ch]) +
;                          w2 * bf2f(cxs[(tok + 2) * 64 + ch]) + w3 * bf2f(cxs[(tok + 3) * 64 + ch]);
;         as_[tok * 64 + ch] = av;
;         bs_[tok * 64 + ch] = mult * ig * xc;
;       }
	s_nop 0
	v_add_f32_e32 v6, v6, v13
	s_waitcnt lgkmcnt(0)
	v_mfma_f32_16x16x32_bf16 v[2:5], v[2:5], v[44:47], v[40:43]
	s_waitcnt vmcnt(0)
	v_mul_f32_e32 v6, 0xbfb8aa3b, v6
	v_exp_f32_e32 v6, v6
	s_nop 0
	v_add_f32_e32 v6, 1.0, v6
	v_rcp_f32_e32 v6, v6
	s_nop 2
	v_add_f32_e32 v2, v2, v12
	v_mul_f32_e32 v6, 0xc1000000, v6
	v_mul_f32_e32 v2, 0xbfb8aa3b, v2
	v_exp_f32_e32 v2, v2
	v_add_f32_e32 v3, v3, v12
	v_mov_b32_e32 v17, v10
	global_load_dword v14, v0, s[40:41] offset:192
	global_load_dword v15, v0, s[40:41] offset:2240
	global_load_dword v16, v[28:29], off offset:192
	global_load_dword v10, v[28:29], off offset:2240
	s_nop 0
	global_load_dword v0, v39, s[46:47] offset:192
	v_mul_f32_e32 v28, v6, v17
	v_mul_f32_e32 v6, 0x3fb8aa3b, v28
	v_add_f32_e32 v28, v28, v28
	v_mul_f32_e32 v28, 0x3fb8aa3b, v28
	v_exp_f32_e32 v28, v28
	ds_read_u16 v39, v31 offset:480
	v_add_f32_e32 v2, 1.0, v2
	v_rcp_f32_e32 v2, v2
	v_sub_f32_e32 v28, 1.0, v28
	v_max_f32_e32 v28, 0, v28
	v_cmp_gt_f32_e32 vcc, s31, v28
	v_mul_f32_e32 v29, 0x4f800000, v28
	v_exp_f32_e32 v6, v6
	v_cndmask_b32_e32 v28, v28, v29, vcc
	v_sqrt_f32_e32 v29, v28
	s_waitcnt lgkmcnt(0)
	v_lshlrev_b32_e32 v39, 16, v39
	ds_write_b32 v37, v6 offset:53952
	v_mul_f32_e32 v3, 0xbfb8aa3b, v3
	v_add_u32_e32 v30, -1, v29
	v_fma_f32 v34, -v30, v29, v28
	v_cmp_ge_f32_e64 s[38:39], 0, v34
	v_add_u32_e32 v34, 1, v29
	v_exp_f32_e32 v3, v3
	v_cndmask_b32_e64 v30, v29, v30, s[38:39]
	v_fma_f32 v29, -v34, v29, v28
	v_cmp_lt_f32_e64 s[38:39], 0, v29
	v_add_f32_e32 v3, 1.0, v3
	v_rcp_f32_e32 v3, v3
	v_cndmask_b32_e64 v29, v30, v34, s[38:39]
	v_mul_f32_e32 v30, 0x37800000, v29
	v_cndmask_b32_e32 v29, v29, v30, vcc
	ds_read_u16 v30, v31 offset:96
	ds_read_u16 v34, v31 offset:224
	v_cmp_class_f32_e32 vcc, v28, v56
	v_add_f32_e32 v4, v4, v12
	v_mul_f32_e32 v4, 0xbfb8aa3b, v4
	v_cndmask_b32_e32 v29, v29, v28, vcc
	v_or_b32_e32 v28, v38, v11
	ds_read_u16 v38, v31 offset:352
	s_waitcnt lgkmcnt(2)
	v_lshlrev_b32_e32 v30, 16, v30
	s_waitcnt lgkmcnt(1)
	v_lshlrev_b32_e32 v34, 16, v34
	v_mul_f32_e32 v2, v2, v29
	v_lshlrev_b32_e32 v6, 2, v28
	s_waitcnt lgkmcnt(0)
	v_lshlrev_b32_e32 v38, 16, v38
	v_add_u32_e32 v28, s4, v6
	v_exp_f32_e32 v4, v4
	s_waitcnt vmcnt(0)
	v_fma_f32 v30, v14, v30, v0
	v_fmac_f32_e32 v30, v15, v34
	v_fmac_f32_e32 v30, v16, v38
	v_fmac_f32_e32 v30, v10, v39
	v_mul_f32_e32 v2, v30, v2
	ds_write_b32 v28, v2
	v_add_f32_e32 v2, v7, v13
	v_mul_f32_e32 v2, 0xbfb8aa3b, v2
	v_exp_f32_e32 v2, v2
	v_fma_f32 v34, v14, v34, v0
	v_fmac_f32_e32 v34, v15, v38
	v_fmac_f32_e32 v34, v16, v39
	v_add_f32_e32 v2, 1.0, v2
	v_rcp_f32_e32 v2, v2
	v_add_f32_e32 v4, 1.0, v4
	v_rcp_f32_e32 v4, v4
	v_mul_f32_e32 v2, 0xc1000000, v2
	v_mul_f32_e32 v2, v2, v17
	v_mul_f32_e32 v7, 0x3fb8aa3b, v2
	v_add_f32_e32 v2, v2, v2
	v_mul_f32_e32 v2, 0x3fb8aa3b, v2
	v_exp_f32_e32 v2, v2
	v_exp_f32_e32 v7, v7
	v_sub_f32_e32 v2, 1.0, v2
	v_max_f32_e32 v2, 0, v2
	v_cmp_gt_f32_e32 vcc, s31, v2
	v_mul_f32_e32 v28, 0x4f800000, v2
	s_nop 0
	v_cndmask_b32_e32 v2, v2, v28, vcc
	v_sqrt_f32_e32 v28, v2
	s_nop 0
	v_add_u32_e32 v29, -1, v28
	v_fma_f32 v30, -v29, v28, v2
	v_cmp_ge_f32_e64 s[38:39], 0, v30
	v_add_u32_e32 v30, 1, v28
	s_nop 0
	v_cndmask_b32_e64 v29, v28, v29, s[38:39]
	v_fma_f32 v28, -v30, v28, v2
	v_cmp_lt_f32_e64 s[38:39], 0, v28
	s_nop 1
	v_cndmask_b32_e64 v28, v29, v30, s[38:39]
	v_mul_f32_e32 v29, 0x37800000, v28
	v_cndmask_b32_e32 v28, v28, v29, vcc
	v_cmp_class_f32_e32 vcc, v2, v56
	v_lshl_add_u32 v30, v11, 1, v35
	v_or_b32_e32 v29, v36, v11
	v_cndmask_b32_e32 v28, v28, v2, vcc
	ds_read_u16 v2, v31 offset:608
	v_mul_f32_e32 v3, v3, v28
	s_waitcnt lgkmcnt(0)
	v_lshlrev_b32_e32 v35, 16, v2
	v_fmac_f32_e32 v34, v10, v35
	v_add_u32_e32 v2, 0, v6
	v_mul_f32_e32 v3, v34, v3
	v_lshl_add_u32 v6, v29, 2, s4
	ds_write_b32 v2, v7 offset:54016
	ds_write_b32 v6, v3
	v_add_f32_e32 v3, v8, v13
	v_mul_f32_e32 v3, 0xbfb8aa3b, v3
	v_exp_f32_e32 v3, v3
	s_nop 0
	v_add_f32_e32 v3, 1.0, v3
	v_rcp_f32_e32 v3, v3
	s_nop 0
	v_mul_f32_e32 v3, 0xc1000000, v3
	v_mul_f32_e32 v3, v3, v17
	v_mul_f32_e32 v6, 0x3fb8aa3b, v3
	v_add_f32_e32 v3, v3, v3
	v_mul_f32_e32 v3, 0x3fb8aa3b, v3
	v_exp_f32_e32 v3, v3
	v_exp_f32_e32 v6, v6
	v_sub_f32_e32 v3, 1.0, v3
	v_max_f32_e32 v3, 0, v3
	v_cmp_gt_f32_e32 vcc, s31, v3
	v_mul_f32_e32 v7, 0x4f800000, v3
	ds_write_b32 v2, v6 offset:54272
	v_cndmask_b32_e32 v3, v3, v7, vcc
	v_sqrt_f32_e32 v7, v3
	s_nop 0
	v_add_u32_e32 v8, -1, v7
	v_fma_f32 v28, -v8, v7, v3
	v_cmp_ge_f32_e64 s[38:39], 0, v28
	v_add_u32_e32 v28, 1, v7
	s_nop 0
	v_cndmask_b32_e64 v8, v7, v8, s[38:39]
	v_fma_f32 v7, -v28, v7, v3
	v_cmp_lt_f32_e64 s[38:39], 0, v7
	s_nop 1
	v_cndmask_b32_e64 v7, v8, v28, s[38:39]
	ds_read_u16 v28, v31 offset:736
	v_mul_f32_e32 v8, 0x37800000, v7
	v_cndmask_b32_e32 v7, v7, v8, vcc
	v_fma_f32 v8, v14, v38, v0
	v_cmp_class_f32_e32 vcc, v3, v56
	v_fmac_f32_e32 v8, v15, v39
	v_fmac_f32_e32 v8, v16, v35
	v_cndmask_b32_e32 v3, v7, v3, vcc
	s_waitcnt lgkmcnt(0)
	v_lshlrev_b32_e32 v28, 16, v28
	v_or_b32_e32 v7, v32, v11
	v_fmac_f32_e32 v8, v10, v28
	v_mul_f32_e32 v3, v4, v3
	v_mul_f32_e32 v3, v8, v3
	v_lshl_add_u32 v4, v7, 2, s4
	ds_write_b32 v4, v3
	v_add_f32_e32 v3, v9, v13
	v_mul_f32_e32 v3, 0xbfb8aa3b, v3
	v_exp_f32_e32 v3, v3
	s_nop 0
	v_add_f32_e32 v3, 1.0, v3
	v_rcp_f32_e32 v4, v3
	v_add_f32_e32 v3, v5, v12
	v_mul_f32_e32 v3, 0xbfb8aa3b, v3
	v_exp_f32_e32 v3, v3
	v_mul_f32_e32 v4, 0xc1000000, v4
	v_mul_f32_e32 v5, v4, v17
	v_mul_f32_e32 v4, 0x3fb8aa3b, v5
	v_add_f32_e32 v5, v5, v5
	v_mul_f32_e32 v5, 0x3fb8aa3b, v5
	v_exp_f32_e32 v5, v5
	v_add_f32_e32 v3, 1.0, v3
	v_rcp_f32_e32 v3, v3
	v_exp_f32_e32 v4, v4
	v_sub_f32_e32 v5, 1.0, v5
	v_max_f32_e32 v5, 0, v5
	v_cmp_gt_f32_e32 vcc, s31, v5
	v_mul_f32_e32 v6, 0x4f800000, v5
	ds_write_b32 v2, v4 offset:54528
	v_cndmask_b32_e32 v5, v5, v6, vcc
	v_sqrt_f32_e32 v6, v5
	s_nop 0
	v_add_u32_e32 v7, -1, v6
	v_fma_f32 v8, -v7, v6, v5
	v_cmp_ge_f32_e64 s[38:39], 0, v8
	v_add_u32_e32 v8, 1, v6
	s_nop 0
	v_cndmask_b32_e64 v7, v6, v7, s[38:39]
	v_fma_f32 v6, -v8, v6, v5
	v_cmp_lt_f32_e64 s[38:39], 0, v6
	s_nop 1
	v_cndmask_b32_e64 v6, v7, v8, s[38:39]
	v_mul_f32_e32 v7, 0x37800000, v6
	v_cndmask_b32_e32 v6, v6, v7, vcc
	ds_read_u16 v7, v30 offset:384
	v_cmp_class_f32_e32 vcc, v5, v56
	s_waitcnt lgkmcnt(0)
	v_lshlrev_b32_e32 v7, 16, v7
	v_fmac_f32_e32 v0, v14, v7
	ds_read_u16 v7, v31 offset:864
	v_fmac_f32_e32 v0, v15, v35
	v_cndmask_b32_e32 v6, v6, v5, vcc
	v_fmac_f32_e32 v0, v16, v28
	v_or_b32_e32 v5, v33, v11
	s_waitcnt lgkmcnt(0)
	v_lshlrev_b32_e32 v7, 16, v7
	v_fmac_f32_e32 v0, v10, v7
	v_mul_f32_e32 v2, v3, v6
	v_mul_f32_e32 v0, v0, v2
	v_lshl_add_u32 v2, v5, 2, s4
	ds_write_b32 v2, v0
	v_or_b32_e32 v0, v25, v71
	v_lshlrev_b32_e32 v0, 2, v0
	v_add_u32_e32 v73, 0, v0
	v_add_u32_e32 v74, s4, v0
	s_waitcnt lgkmcnt(0)
	s_barrier
; template <int APPLY>
; __device__ void lru_item(PP p, int l, int bb, int ck, int nb, unsigned epoch) {
;     ...
;   {
;     const int ch = tid & 63, seg = tid >> 6;
;     float P = 1.f, hh = 0.f;
; #pragma unroll
;     for (int i = 0; i < 16; ++i) {
;       const int idx = (seg * 16 + i) * 64 + ch;
;       const float a = as_[idx], b = bs_[idx];
;       hh = a * hh + b; P *= a;
;       as_[idx] = P; bs_[idx] = hh;
;     }
;     segA[seg * 64 + ch] = P; segH[seg * 64 + ch] = hh;
;   }
;   __syncthreads();
;   if (APPLY == 2) {
;     unsigned long long* tg = p->lruT + ((long)(bb * 64) * 512 + nb * 64) * 2;
;     if (tid < 64) {
;       const int ch = tid;
;       float hl = 0.f, At = 1.f;
; #pragma unroll
;       for (int sg = 0; sg < 8; ++sg) { const float a = segA[sg * 64 + ch]; hl = a * hl + segH[sg * 64 + ch]; At *= a; }
;       unsigned long long* dst = tg + ((long)ck * 512 + ch) * 2;
;       __hip_atomic_store(dst, ((unsigned long long)epoch << 32) | __float_as_uint(At), __ATOMIC_RELAXED, __HIP_MEMORY_SCOPE_AGENT);
;       __hip_atomic_store(dst + 1, ((unsigned long long)epoch << 32) | __float_as_uint(hl), __ATOMIC_RELAXED, __HIP_MEMORY_SCOPE_AGENT);
;     }
	ds_read2st64_b32 v[2:3], v73 offset0:210 offset1:211
	ds_read2st64_b32 v[4:5], v74 offset1:1
	s_lshl_b32 s4, s59, 16
	s_or_b32 s92, s4, s52
	s_lshl_b64 s[4:5], s[92:93], 3
	s_add_u32 s38, s42, s4
	s_waitcnt lgkmcnt(0)
	v_fma_f32 v0, 0, v2, v4
	v_fmac_f32_e32 v5, v0, v3
	ds_write2st64_b32 v74, v0, v5 offset1:1
	v_mul_f32_e32 v4, v2, v3
	ds_read2st64_b32 v[2:3], v73 offset0:212 offset1:213
	ds_read2st64_b32 v[6:7], v74 offset0:2 offset1:3
	s_addc_u32 s39, s43, s5
	v_cmp_gt_i32_e32 vcc, 64, v24
	s_waitcnt lgkmcnt(0)
	v_fma_f32 v0, v5, v2, v6
	v_mul_f32_e32 v2, v4, v2
	v_fmac_f32_e32 v7, v0, v3
	ds_write2st64_b32 v73, v4, v2 offset0:211 offset1:212
	ds_write2st64_b32 v74, v0, v7 offset0:2 offset1:3
	v_mul_f32_e32 v6, v2, v3
	ds_read2st64_b32 v[2:3], v73 offset0:214 offset1:215
	ds_read2st64_b32 v[4:5], v74 offset0:4 offset1:5
	s_waitcnt lgkmcnt(0)
	v_fma_f32 v0, v7, v2, v4
	v_mul_f32_e32 v2, v6, v2
	v_fmac_f32_e32 v5, v0, v3
	ds_write2st64_b32 v73, v6, v2 offset0:213 offset1:214
	ds_write2st64_b32 v74, v0, v5 offset0:4 offset1:5
	v_mul_f32_e32 v4, v2, v3
	ds_read2st64_b32 v[2:3], v73 offset0:216 offset1:217
	ds_read2st64_b32 v[6:7], v74 offset0:6 offset1:7
	s_waitcnt lgkmcnt(0)
	v_fma_f32 v0, v5, v2, v6
	v_mul_f32_e32 v2, v4, v2
	v_fmac_f32_e32 v7, v0, v3
	ds_write2st64_b32 v73, v4, v2 offset0:215 offset1:216
	ds_write2st64_b32 v74, v0, v7 offset0:6 offset1:7
	v_mul_f32_e32 v6, v2, v3
	ds_read2st64_b32 v[2:3], v73 offset0:218 offset1:219
	ds_read2st64_b32 v[4:5], v74 offset0:8 offset1:9
	s_waitcnt lgkmcnt(0)
	v_fma_f32 v0, v7, v2, v4
	v_mul_f32_e32 v2, v6, v2
	v_fmac_f32_e32 v5, v0, v3
	ds_write2st64_b32 v73, v6, v2 offset0:217 offset1:218
	ds_write2st64_b32 v74, v0, v5 offset0:8 offset1:9
	v_mul_f32_e32 v4, v2, v3
	ds_read2st64_b32 v[2:3], v73 offset0:220 offset1:221
	ds_read2st64_b32 v[6:7], v74 offset0:10 offset1:11
	s_waitcnt lgkmcnt(0)
	v_fma_f32 v0, v5, v2, v6
	v_mul_f32_e32 v2, v4, v2
	v_fmac_f32_e32 v7, v0, v3
	ds_write2st64_b32 v73, v4, v2 offset0:219 offset1:220
	ds_write2st64_b32 v74, v0, v7 offset0:10 offset1:11
	v_mul_f32_e32 v6, v2, v3
	ds_read2st64_b32 v[2:3], v73 offset0:222 offset1:223
	ds_read2st64_b32 v[4:5], v74 offset0:12 offset1:13
	s_waitcnt lgkmcnt(0)
	v_fma_f32 v0, v7, v2, v4
	v_mul_f32_e32 v2, v6, v2
	v_fmac_f32_e32 v5, v0, v3
	ds_write2st64_b32 v73, v6, v2 offset0:221 offset1:222
	ds_write2st64_b32 v74, v0, v5 offset0:12 offset1:13
	v_mul_f32_e32 v4, v2, v3
	ds_read2st64_b32 v[2:3], v73 offset0:224 offset1:225
	ds_read2st64_b32 v[6:7], v74 offset0:14 offset1:15
	s_waitcnt lgkmcnt(0)
	v_fma_f32 v0, v5, v2, v6
	v_mul_f32_e32 v2, v4, v2
	ds_write2st64_b32 v73, v4, v2 offset0:223 offset1:224
	v_mul_f32_e32 v2, v2, v3
	v_fmac_f32_e32 v7, v0, v3
	ds_write_b32 v73, v2 offset:57600
	ds_write2st64_b32 v74, v0, v7 offset0:14 offset1:15
	v_lshl_add_u32 v0, v24, 2, 0
	v_add_u32_e32 v76, 0x1d200, v0
	v_add_u32_e32 v75, 0x1da00, v0
	ds_write_b32 v76, v2
	ds_write_b32 v75, v7
	s_waitcnt lgkmcnt(0)
	s_barrier
	s_and_saveexec_b64 s[40:41], vcc
	s_cbranch_execz .LBB0_124
	ds_read2st64_b32 v[2:3], v76 offset1:1
	ds_read2st64_b32 v[4:5], v75 offset1:1
	v_ashrrev_i32_e32 v25, 31, v24
	s_lshl_b32 s92, s58, 9
	s_waitcnt lgkmcnt(0)
	v_fma_f32 v4, 0, v2, v4
	v_fmac_f32_e32 v5, v4, v3
	v_mul_f32_e32 v4, v2, v3
	ds_read2st64_b32 v[2:3], v76 offset0:2 offset1:3
	ds_read2st64_b32 v[6:7], v75 offset0:2 offset1:3
	s_waitcnt lgkmcnt(0)
	v_fma_f32 v5, v5, v2, v6
	v_mul_f32_e32 v2, v4, v2
	v_fmac_f32_e32 v7, v5, v3
	v_mul_f32_e32 v6, v2, v3
	ds_read2st64_b32 v[2:3], v76 offset0:4 offset1:5
	ds_read2st64_b32 v[4:5], v75 offset0:4 offset1:5
	s_waitcnt lgkmcnt(0)
	v_fma_f32 v4, v7, v2, v4
	v_mul_f32_e32 v2, v6, v2
	v_fmac_f32_e32 v5, v4, v3
	v_mul_f32_e32 v4, v2, v3
	ds_read2st64_b32 v[2:3], v76 offset0:6 offset1:7
	ds_read2st64_b32 v[6:7], v75 offset0:6 offset1:7
	s_waitcnt lgkmcnt(0)
	v_fma_f32 v5, v5, v2, v6
	v_mul_f32_e32 v2, v4, v2
	v_fmac_f32_e32 v7, v5, v3
	v_lshl_add_u64 v[4:5], v[24:25], 0, s[92:93]
	v_mul_f32_e32 v2, v2, v3
	v_lshl_add_u64 v[4:5], v[4:5], 4, s[38:39]
	v_mov_b32_e32 v3, s71
	global_store_dwordx2 v[4:5], v[2:3], off sc1
	v_mov_b32_e32 v2, v7
	global_store_dwordx2 v[4:5], v[2:3], off offset:8 sc1

; template <int APPLY>
; __device__ void lru_item(PP p, int l, int bb, int ck, int nb, unsigned epoch) {
;     ...
;       const float sp = log1pf(__expf(-p->lru_lambda[l * 512 + gch]));
.LBB0_575:
	s_getreg_b32 s98, hwreg(HW_REG_HW_ID, 0, 6)
	s_lshl_b32 s98, s98, 2
	s_and_b32 s98, s98, 0xfc
	s_add_i32 s98, s98, 0x21c00
	v_mov_b32_e32 v117, s98
	ds_read_b32 v117, v117
	v_mbcnt_lo_u32_b32 v118, -1, 0
	v_mbcnt_hi_u32_b32 v118, -1, v118
	s_load_dwordx2 s[98:99], s[0:1], 0x68
	s_load_dwordx2 s[100:101], s[0:1], 0xf8
	s_waitcnt lgkmcnt(0)
	v_lshl_add_u32 v117, v117, 6, v118
	v_lshlrev_b32_e32 v117, 2, v117
	global_load_dword v100, v117, s[98:99]
	global_load_dword v119, v117, s[98:99] offset:2048
	v_mov_b32_e32 v113, 0x3ecc95a3
	v_mov_b32_e32 v114, 0x7f800000
	v_mov_b32_e32 v115, 0x7fc00000
	v_mov_b32_e32 v116, 0xff800000
	v_mov_b32_e32 v120, 0x3f2aaaab
	v_mov_b32_e32 v121, 0x3f317218
	v_mov_b32_e32 v122, 0x7f800000
	v_mov_b32_e32 v123, 0x33800000
	s_waitcnt vmcnt(0)
	v_mul_f32_e32 v100, 0xbfb8aa3b, v100
	v_exp_f32_e32 v100, v100
	s_nop 0
	v_add_f32_e32 v101, 1.0, v100
	v_add_f32_e32 v102, -1.0, v101
	v_sub_f32_e32 v103, v102, v101
	v_add_f32_e32 v103, 1.0, v103
	v_sub_f32_e32 v102, v100, v102
	v_add_f32_e32 v105, v102, v103
	v_frexp_mant_f32_e32 v102, v101
	v_cmp_gt_f32_e32 vcc, v120, v102
	v_cvt_f64_f32_e32 v[102:103], v101
	v_frexp_exp_i32_f64_e32 v102, v[102:103]
	v_subbrev_co_u32_e32 v102, vcc, 0, v102, vcc
	v_sub_u32_e32 v103, 0, v102
	v_ldexp_f32 v101, v101, v103
	v_ldexp_f32 v103, v105, v103
	v_add_f32_e32 v105, -1.0, v101
	v_cvt_f32_i32_e32 v102, v102
	v_cmp_neq_f32_e32 vcc, v122, v100
	v_add_f32_e32 v106, 1.0, v105
	v_sub_f32_e32 v106, v101, v106
	v_add_f32_e32 v106, v103, v106
	v_add_f32_e32 v107, v105, v106
	v_sub_f32_e32 v105, v107, v105
	v_sub_f32_e32 v105, v106, v105
	v_add_f32_e32 v106, 1.0, v101
	v_add_f32_e32 v108, -1.0, v106
	v_sub_f32_e32 v101, v101, v108
	v_add_f32_e32 v101, v103, v101
	v_add_f32_e32 v103, v106, v101
	v_sub_f32_e32 v106, v103, v106
	v_sub_f32_e32 v101, v101, v106
	v_rcp_f32_e32 v106, v103
	s_nop 0
	v_mul_f32_e32 v108, v107, v106
	v_mul_f32_e32 v109, v103, v108
	v_fma_f32 v110, v108, v103, -v109
	v_fmac_f32_e32 v110, v108, v101
	v_add_f32_e32 v111, v109, v110
	v_sub_f32_e32 v112, v107, v111
	v_sub_f32_e32 v107, v107, v112
	v_sub_f32_e32 v109, v111, v109
	v_sub_f32_e32 v107, v107, v111
	v_add_f32_e32 v105, v105, v107
	v_sub_f32_e32 v107, v109, v110
	v_add_f32_e32 v105, v107, v105
	v_add_f32_e32 v107, v112, v105
	v_mul_f32_e32 v109, v106, v107
	v_mul_f32_e32 v110, v103, v109
	v_fma_f32 v103, v109, v103, -v110
	v_fmac_f32_e32 v103, v109, v101
	v_sub_f32_e32 v101, v112, v107
	v_add_f32_e32 v101, v105, v101
	v_add_f32_e32 v105, v110, v103
	v_sub_f32_e32 v111, v107, v105
	v_sub_f32_e32 v107, v107, v111
	v_sub_f32_e32 v110, v105, v110
	v_sub_f32_e32 v105, v107, v105
	v_add_f32_e32 v101, v101, v105
	v_sub_f32_e32 v103, v110, v103
	v_add_f32_e32 v101, v103, v101
	v_add_f32_e32 v103, v108, v109
	v_add_f32_e32 v101, v111, v101
	v_sub_f32_e32 v105, v103, v108
	v_mul_f32_e32 v101, v106, v101
	v_sub_f32_e32 v105, v109, v105
	v_add_f32_e32 v101, v105, v101
	v_mul_f32_e32 v108, 0x3f317218, v102
	v_add_f32_e32 v105, v103, v101
	v_fma_f32 v109, v102, v121, -v108
	v_mul_f32_e32 v106, v105, v105
	v_fmac_f32_e32 v109, 0xb102e308, v102
	v_sub_f32_e32 v102, v105, v103
	v_fmamk_f32 v107, v106, 0x3e9b6dac, v113
	v_sub_f32_e32 v101, v101, v102
	v_add_f32_e32 v102, v108, v109
	v_fmaak_f32 v107, v106, v107, 0x3f2aaada
	v_sub_f32_e32 v103, v102, v108
	v_ldexp_f32 v108, v105, 1
	v_mul_f32_e32 v105, v105, v106
	v_mul_f32_e32 v105, v105, v107
	v_add_f32_e32 v106, v108, v105
	v_sub_f32_e32 v107, v106, v108
	v_ldexp_f32 v101, v101, 1
	v_sub_f32_e32 v105, v105, v107
	v_add_f32_e32 v101, v101, v105
	v_add_f32_e32 v105, v106, v101
	v_sub_f32_e32 v106, v105, v106
	v_sub_f32_e32 v101, v101, v106
	v_add_f32_e32 v106, v102, v105
	v_sub_f32_e32 v107, v106, v102
	v_sub_f32_e32 v108, v106, v107
	v_sub_f32_e32 v103, v109, v103
	v_sub_f32_e32 v102, v102, v108
	v_sub_f32_e32 v105, v105, v107
	v_add_f32_e32 v102, v105, v102
	v_add_f32_e32 v105, v103, v101
	v_sub_f32_e32 v107, v105, v103
	v_sub_f32_e32 v108, v105, v107
	v_sub_f32_e32 v103, v103, v108
	v_sub_f32_e32 v101, v101, v107
	v_add_f32_e32 v102, v105, v102
	v_add_f32_e32 v101, v101, v103
	v_add_f32_e32 v103, v106, v102
	v_sub_f32_e32 v105, v103, v106
	v_sub_f32_e32 v102, v102, v105
	v_add_f32_e32 v101, v101, v102
	v_add_f32_e32 v101, v103, v101
	v_cndmask_b32_e32 v101, v114, v101, vcc
	v_cmp_ngt_f32_e32 vcc, -1.0, v100
	v_cndmask_b32_e32 v101, v115, v101, vcc
; template <int APPLY>
; __device__ void lru_item(PP p, int l, int bb, int ck, int nb, unsigned epoch) {
;     ...
;       const float sp = log1pf(__expf(-p->lru_lambda[l * 512 + gch]));
	v_cmp_neq_f32_e32 vcc, -1.0, v100
	v_cndmask_b32_e32 v101, v116, v101, vcc
	v_cmp_lt_f32_e64 vcc, |v100|, v123
	v_cndmask_b32_e32 v103, v101, v100, vcc
	global_store_dword v117, v103, s[100:101]
	v_mov_b32_e32 v100, v119
	s_nop 0
	v_mul_f32_e32 v100, 0xbfb8aa3b, v100
	v_exp_f32_e32 v100, v100
	s_nop 0
	v_add_f32_e32 v101, 1.0, v100
	v_add_f32_e32 v102, -1.0, v101
	v_sub_f32_e32 v103, v102, v101
	v_add_f32_e32 v103, 1.0, v103
	v_sub_f32_e32 v102, v100, v102
	v_add_f32_e32 v105, v102, v103
	v_frexp_mant_f32_e32 v102, v101
	v_cmp_gt_f32_e32 vcc, v120, v102
	v_cvt_f64_f32_e32 v[102:103], v101
	v_frexp_exp_i32_f64_e32 v102, v[102:103]
	v_subbrev_co_u32_e32 v102, vcc, 0, v102, vcc
	v_sub_u32_e32 v103, 0, v102
	v_ldexp_f32 v101, v101, v103
	v_ldexp_f32 v103, v105, v103
	v_add_f32_e32 v105, -1.0, v101
	v_cvt_f32_i32_e32 v102, v102
	v_cmp_neq_f32_e32 vcc, v122, v100
	v_add_f32_e32 v106, 1.0, v105
	v_sub_f32_e32 v106, v101, v106
	v_add_f32_e32 v106, v103, v106
	v_add_f32_e32 v107, v105, v106
	v_sub_f32_e32 v105, v107, v105
	v_sub_f32_e32 v105, v106, v105
	v_add_f32_e32 v106, 1.0, v101
	v_add_f32_e32 v108, -1.0, v106
	v_sub_f32_e32 v101, v101, v108
	v_add_f32_e32 v101, v103, v101
	v_add_f32_e32 v103, v106, v101
	v_sub_f32_e32 v106, v103, v106
	v_sub_f32_e32 v101, v101, v106
	v_rcp_f32_e32 v106, v103
	s_nop 0
	v_mul_f32_e32 v108, v107, v106
	v_mul_f32_e32 v109, v103, v108
	v_fma_f32 v110, v108, v103, -v109
	v_fmac_f32_e32 v110, v108, v101
	v_add_f32_e32 v111, v109, v110
	v_sub_f32_e32 v112, v107, v111
	v_sub_f32_e32 v107, v107, v112
	v_sub_f32_e32 v109, v111, v109
	v_sub_f32_e32 v107, v107, v111
	v_add_f32_e32 v105, v105, v107
	v_sub_f32_e32 v107, v109, v110
	v_add_f32_e32 v105, v107, v105
	v_add_f32_e32 v107, v112, v105
	v_mul_f32_e32 v109, v106, v107
	v_mul_f32_e32 v110, v103, v109
	v_fma_f32 v103, v109, v103, -v110
	v_fmac_f32_e32 v103, v109, v101
	v_sub_f32_e32 v101, v112, v107
	v_add_f32_e32 v101, v105, v101
	v_add_f32_e32 v105, v110, v103
	v_sub_f32_e32 v111, v107, v105
	v_sub_f32_e32 v107, v107, v111
	v_sub_f32_e32 v110, v105, v110
	v_sub_f32_e32 v105, v107, v105
	v_add_f32_e32 v101, v101, v105
	v_sub_f32_e32 v103, v110, v103
	v_add_f32_e32 v101, v103, v101
	v_add_f32_e32 v103, v108, v109
	v_add_f32_e32 v101, v111, v101
	v_sub_f32_e32 v105, v103, v108
	v_mul_f32_e32 v101, v106, v101
	v_sub_f32_e32 v105, v109, v105
	v_add_f32_e32 v101, v105, v101
	v_mul_f32_e32 v108, 0x3f317218, v102
	v_add_f32_e32 v105, v103, v101
	v_fma_f32 v109, v102, v121, -v108
	v_mul_f32_e32 v106, v105, v105
	v_fmac_f32_e32 v109, 0xb102e308, v102
	v_sub_f32_e32 v102, v105, v103
	v_fmamk_f32 v107, v106, 0x3e9b6dac, v113
	v_sub_f32_e32 v101, v101, v102
	v_add_f32_e32 v102, v108, v109
	v_fmaak_f32 v107, v106, v107, 0x3f2aaada
	v_sub_f32_e32 v103, v102, v108
	v_ldexp_f32 v108, v105, 1
	v_mul_f32_e32 v105, v105, v106
	v_mul_f32_e32 v105, v105, v107
	v_add_f32_e32 v106, v108, v105
	v_sub_f32_e32 v107, v106, v108
	v_ldexp_f32 v101, v101, 1
	v_sub_f32_e32 v105, v105, v107
	v_add_f32_e32 v101, v101, v105
	v_add_f32_e32 v105, v106, v101
	v_sub_f32_e32 v106, v105, v106
	v_sub_f32_e32 v101, v101, v106
	v_add_f32_e32 v106, v102, v105
	v_sub_f32_e32 v107, v106, v102
	v_sub_f32_e32 v108, v106, v107
	v_sub_f32_e32 v103, v109, v103
	v_sub_f32_e32 v102, v102, v108
	v_sub_f32_e32 v105, v105, v107
	v_add_f32_e32 v102, v105, v102
	v_add_f32_e32 v105, v103, v101
	v_sub_f32_e32 v107, v105, v103
	v_sub_f32_e32 v108, v105, v107
	v_sub_f32_e32 v103, v103, v108
	v_sub_f32_e32 v101, v101, v107
	v_add_f32_e32 v102, v105, v102
	v_add_f32_e32 v101, v101, v103
	v_add_f32_e32 v103, v106, v102
	v_sub_f32_e32 v105, v103, v106
	v_sub_f32_e32 v102, v102, v105
	v_add_f32_e32 v101, v101, v102
	v_add_f32_e32 v101, v103, v101
	v_cndmask_b32_e32 v101, v114, v101, vcc
	v_cmp_ngt_f32_e32 vcc, -1.0, v100
	v_cndmask_b32_e32 v101, v115, v101, vcc
	v_cmp_neq_f32_e32 vcc, -1.0, v100
	v_cndmask_b32_e32 v101, v116, v101, vcc
	v_cmp_lt_f32_e64 vcc, |v100|, v123
	v_cndmask_b32_e32 v103, v101, v100, vcc
	global_store_dword v117, v103, s[100:101] offset:2048
	s_mov_b32 s2, 1
	s_cmp_lt_i32 s2, 1
	s_cbranch_scc1 .LBB0_9
	s_add_u32 s6, s0, 8
	s_addc_u32 s7, s1, 0
	s_add_u32 s10, s0, 0xd0
	s_addc_u32 s11, s1, 0
	s_add_u32 s44, s0, 0xf0
	s_addc_u32 s45, s1, 0
	s_add_u32 s46, s0, 0xc8
	s_addc_u32 s47, s1, 0
	s_add_u32 s48, s0, 0xe8
	s_addc_u32 s49, s1, 0
	s_mov_b32 s74, 0
	s_branch .LBB0_578

; __global__ void __launch_bounds__(512) mega(Params p_arg, int ph_lo, int ph_hi) {
	.amdhsa_kernel _Z4mega6Paramsii
		.amdhsa_group_segment_fixed_size 0
		.amdhsa_private_segment_fixed_size 0
		.amdhsa_kernarg_size 568
		.amdhsa_user_sgpr_count 2
		.amdhsa_user_sgpr_dispatch_ptr 0
		.amdhsa_user_sgpr_queue_ptr 0
		.amdhsa_user_sgpr_kernarg_segment_ptr 1
		.amdhsa_user_sgpr_dispatch_id 0
		.amdhsa_user_sgpr_kernarg_preload_length 0
		.amdhsa_user_sgpr_kernarg_preload_offset 0
		.amdhsa_user_sgpr_private_segment_size 0
		.amdhsa_uses_dynamic_stack 0
		.amdhsa_enable_private_segment 0
		.amdhsa_system_sgpr_workgroup_id_x 1
		.amdhsa_system_sgpr_workgroup_id_y 0
		.amdhsa_system_sgpr_workgroup_id_z 0
		.amdhsa_system_sgpr_workgroup_info 0
		.amdhsa_system_vgpr_workitem_id 2
		.amdhsa_next_free_vgpr 256
		.amdhsa_next_free_sgpr 102
		.amdhsa_accum_offset 256
		.amdhsa_reserve_vcc 1
		.amdhsa_float_round_mode_32 0
		.amdhsa_float_round_mode_16_64 0
		.amdhsa_float_denorm_mode_32 3
		.amdhsa_float_denorm_mode_16_64 3
		.amdhsa_dx10_clamp 1
		.amdhsa_ieee_mode 1
		.amdhsa_fp16_overflow 0
		.amdhsa_tg_split 0
		.amdhsa_exception_fp_ieee_invalid_op 0
		.amdhsa_exception_fp_denorm_src 0
		.amdhsa_exception_fp_ieee_div_zero 0
		.amdhsa_exception_fp_ieee_overflow 0
		.amdhsa_exception_fp_ieee_underflow 0
		.amdhsa_exception_fp_ieee_inexact 0
		.amdhsa_exception_int_div_zero 0
	.end_amdhsa_kernel

; __global__ void __launch_bounds__(512) mega(Params p_arg, int ph_lo, int ph_hi) {
amdhsa.kernels:
  - .agpr_count:     0
    .args:
      - .offset:         0
        .size:           304
        .value_kind:     by_value
      - .offset:         304
        .size:           4
        .value_kind:     by_value
      - .offset:         308
        .size:           4
        .value_kind:     by_value
      - .offset:         312
        .size:           4
        .value_kind:     hidden_block_count_x
      - .offset:         316
        .size:           4
        .value_kind:     hidden_block_count_y
      - .offset:         320
        .size:           4
        .value_kind:     hidden_block_count_z
      - .offset:         324
        .size:           2
        .value_kind:     hidden_group_size_x
      - .offset:         326
        .size:           2
        .value_kind:     hidden_group_size_y
      - .offset:         328
        .size:           2
        .value_kind:     hidden_group_size_z
      - .offset:         330
        .size:           2
        .value_kind:     hidden_remainder_x
      - .offset:         332
        .size:           2
        .value_kind:     hidden_remainder_y
      - .offset:         334
        .size:           2
        .value_kind:     hidden_remainder_z
      - .offset:         352
        .size:           8
        .value_kind:     hidden_global_offset_x
      - .offset:         360
        .size:           8
        .value_kind:     hidden_global_offset_y
      - .offset:         368
        .size:           8
        .value_kind:     hidden_global_offset_z
      - .offset:         376
        .size:           2
        .value_kind:     hidden_grid_dims
      - .offset:         400
        .size:           8
        .value_kind:     hidden_multigrid_sync_arg
      - .offset:         432
        .size:           4
        .value_kind:     hidden_dynamic_lds_size
    .group_segment_fixed_size: 0
    .kernarg_segment_align: 8
    .kernarg_segment_size: 568
    .language:       OpenCL C
    .language_version:
      - 2
      - 0
    .max_flat_workgroup_size: 512
    .name:           _Z4mega6Paramsii
    .private_segment_fixed_size: 0
    .sgpr_count:     108
    .sgpr_spill_count: 124
    .symbol:         _Z4mega6Paramsii.kd
    .uniform_work_group_size: 1
    .uses_dynamic_stack: false
    .vgpr_count:     256
    .vgpr_spill_count: 0
    .wavefront_size: 64
